# DSA PV gather index reads batched; inproj epilogue rewritten with SGPR-base addressing and packed transposed stores
# speedup vs baseline: 1.1011x; 1.0185x over previous
; template <class LA, class LB, class EP>
; __device__ __forceinline__ void gemm_tile_big(int K, LA loadA, LB loadB, EP epi, char* smem) {
;     ...
;   for (int kt = 0; kt < nk; ++kt) {
;     __syncthreads();
; #pragma unroll
;     for (int i = 0; i < 8; ++i) *(uint4*)&sA[(lr + 32 * i) * 72 + lc] = ra[i];
; #pragma unroll
;     for (int i = 0; i < 4; ++i) *(uint4*)&sB[(lr + 32 * i) * 72 + lc] = rb[i];
;     __syncthreads();
;     if (kt + 1 < nk) {
;       const int kk = (kt + 1) * 64 + lc;
; #pragma unroll
;       for (int i = 0; i < 8; ++i) ra[i] = loadA(lr + 32 * i, kk);
; #pragma unroll
;       for (int i = 0; i < 4; ++i) rb[i] = loadB(lr + 32 * i, kk);
;     }
; #pragma unroll
;     for (int s = 0; s < 4; ++s) {
;       h8 af[4], bf[2];
; #pragma unroll
;       for (int mi = 0; mi < 4; ++mi)
;         af[mi] = *(const h8*)&sA[(wm * 128 + mi * 32 + (lane & 31)) * 72 + s * 16 + (lane >> 5) * 8];
; #pragma unroll
;       for (int ni = 0; ni < 2; ++ni)
;         bf[ni] = *(const h8*)&sB[(wn * 64 + ni * 32 + (lane & 31)) * 72 + s * 16 + (lane >> 5) * 8];
; #pragma unroll
;       for (int mi = 0; mi < 4; ++mi)
; #pragma unroll
;         for (int ni = 0; ni < 2; ++ni)
;           acc[mi][ni] = __builtin_amdgcn_mfma_f32_32x32x16_f16(af[mi], bf[ni], acc[mi][ni], 0, 0, 0);
;     }
;   }
.Lgp1_loop:
	ds_read_b128 v[238:241], v179 offset:20480
	ds_read_b128 v[242:245], v179 offset:23040
	ds_read_b128 v[200:203], v178
	ds_read_b128 v[204:207], v178 offset:2560
	ds_read_b128 v[214:217], v178 offset:5120
	ds_read_b128 v[218:221], v178 offset:7680
	global_load_dwordx4 v[130:133], v208, s[38:39]
	global_load_dwordx4 v[134:137], v209, s[38:39]
	global_load_dwordx4 v[138:141], v210, s[38:39]
	global_load_dwordx4 v[142:145], v211, s[38:39]
	global_load_dwordx4 v[146:149], v208, s[2:3]
	global_load_dwordx4 v[150:153], v209, s[2:3]
	s_add_u32 s38, s38, 64
	s_addc_u32 s39, s39, 0
	s_add_u32 s2, s2, 64
	s_addc_u32 s3, s3, 0
	ds_read_b128 v[226:229], v179 offset:20512
	ds_read_b128 v[230:233], v179 offset:23072
	s_waitcnt lgkmcnt(5)
	v_mfma_f32_32x32x16_f16 v[114:129], v[200:203], v[238:241], v[114:129]
	v_mfma_f32_32x32x16_f16 v[98:113], v[200:203], v[242:245], v[98:113]
	ds_read_b128 v[200:203], v178 offset:32
	s_waitcnt lgkmcnt(5)
	v_mfma_f32_32x32x16_f16 v[82:97], v[204:207], v[238:241], v[82:97]
	v_mfma_f32_32x32x16_f16 v[66:81], v[204:207], v[242:245], v[66:81]
	ds_read_b128 v[204:207], v178 offset:2592
	s_waitcnt vmcnt(11)
	ds_write_b128 v196, v[154:157] offset:30720
	s_waitcnt lgkmcnt(6)
	v_mfma_f32_32x32x16_f16 v[50:65], v[214:217], v[238:241], v[50:65]
	v_mfma_f32_32x32x16_f16 v[34:49], v[214:217], v[242:245], v[34:49]
	ds_read_b128 v[214:217], v178 offset:5152
	s_waitcnt vmcnt(10)
	ds_write_b128 v196, v[158:161] offset:35840
	s_waitcnt lgkmcnt(7)
	v_mfma_f32_32x32x16_f16 v[18:33], v[218:221], v[238:241], v[18:33]
	v_mfma_f32_32x32x16_f16 v[2:17], v[218:221], v[242:245], v[2:17]
	ds_read_b128 v[218:221], v178 offset:7712
	s_waitcnt vmcnt(9)
	ds_write_b128 v196, v[162:165] offset:40960
	s_waitcnt lgkmcnt(6)
	v_mfma_f32_32x32x16_f16 v[114:129], v[200:203], v[226:229], v[114:129]
	v_mfma_f32_32x32x16_f16 v[98:113], v[200:203], v[230:233], v[98:113]
	s_waitcnt vmcnt(8)
	ds_write_b128 v196, v[166:169] offset:46080
	s_waitcnt lgkmcnt(6)
	v_mfma_f32_32x32x16_f16 v[82:97], v[204:207], v[226:229], v[82:97]
	v_mfma_f32_32x32x16_f16 v[66:81], v[204:207], v[230:233], v[66:81]
	s_waitcnt vmcnt(7)
	ds_write_b128 v196, v[170:173] offset:51200
	s_waitcnt lgkmcnt(5)
	v_mfma_f32_32x32x16_f16 v[50:65], v[214:217], v[226:229], v[50:65]
	v_mfma_f32_32x32x16_f16 v[34:49], v[214:217], v[230:233], v[34:49]
	s_waitcnt vmcnt(6)
	ds_write_b128 v196, v[174:177] offset:56320
	s_waitcnt lgkmcnt(4)
	v_mfma_f32_32x32x16_f16 v[18:33], v[218:221], v[226:229], v[18:33]
	v_mfma_f32_32x32x16_f16 v[2:17], v[218:221], v[230:233], v[2:17]
	s_waitcnt lgkmcnt(0)
	s_barrier
	ds_read_b128 v[238:241], v179 offset:51200
	ds_read_b128 v[242:245], v179 offset:53760
	ds_read_b128 v[200:203], v178 offset:30720
	ds_read_b128 v[204:207], v178 offset:33280
	ds_read_b128 v[214:217], v178 offset:35840
	ds_read_b128 v[218:221], v178 offset:38400
	global_load_dwordx4 v[154:157], v208, s[38:39]
	global_load_dwordx4 v[158:161], v209, s[38:39]
	global_load_dwordx4 v[162:165], v210, s[38:39]
	global_load_dwordx4 v[166:169], v211, s[38:39]
	global_load_dwordx4 v[170:173], v208, s[2:3]
	global_load_dwordx4 v[174:177], v209, s[2:3]
	s_add_u32 s38, s38, 64
	s_addc_u32 s39, s39, 0
	s_add_u32 s2, s2, 64
	s_addc_u32 s3, s3, 0
	ds_read_b128 v[226:229], v179 offset:51232
	ds_read_b128 v[230:233], v179 offset:53792
	s_waitcnt lgkmcnt(5)
	v_mfma_f32_32x32x16_f16 v[114:129], v[200:203], v[238:241], v[114:129]
	v_mfma_f32_32x32x16_f16 v[98:113], v[200:203], v[242:245], v[98:113]
	ds_read_b128 v[200:203], v178 offset:30752
	s_waitcnt lgkmcnt(5)
	v_mfma_f32_32x32x16_f16 v[82:97], v[204:207], v[238:241], v[82:97]
	v_mfma_f32_32x32x16_f16 v[66:81], v[204:207], v[242:245], v[66:81]
	ds_read_b128 v[204:207], v178 offset:33312
	s_waitcnt vmcnt(11)
	ds_write_b128 v196, v[130:133]
	s_waitcnt lgkmcnt(6)
	v_mfma_f32_32x32x16_f16 v[50:65], v[214:217], v[238:241], v[50:65]
	v_mfma_f32_32x32x16_f16 v[34:49], v[214:217], v[242:245], v[34:49]
	ds_read_b128 v[214:217], v178 offset:35872
	s_waitcnt vmcnt(10)
	ds_write_b128 v196, v[134:137] offset:5120
	s_waitcnt lgkmcnt(7)
	v_mfma_f32_32x32x16_f16 v[18:33], v[218:221], v[238:241], v[18:33]
	v_mfma_f32_32x32x16_f16 v[2:17], v[218:221], v[242:245], v[2:17]
	ds_read_b128 v[218:221], v178 offset:38432
	s_waitcnt vmcnt(9)
	ds_write_b128 v196, v[138:141] offset:10240
	s_waitcnt lgkmcnt(6)
	v_mfma_f32_32x32x16_f16 v[114:129], v[200:203], v[226:229], v[114:129]
	v_mfma_f32_32x32x16_f16 v[98:113], v[200:203], v[230:233], v[98:113]
	s_waitcnt vmcnt(8)
	ds_write_b128 v196, v[142:145] offset:15360
	s_waitcnt lgkmcnt(6)
	v_mfma_f32_32x32x16_f16 v[82:97], v[204:207], v[226:229], v[82:97]
	v_mfma_f32_32x32x16_f16 v[66:81], v[204:207], v[230:233], v[66:81]
	s_waitcnt vmcnt(7)
	ds_write_b128 v196, v[146:149] offset:20480
	s_waitcnt lgkmcnt(5)
	v_mfma_f32_32x32x16_f16 v[50:65], v[214:217], v[226:229], v[50:65]
	v_mfma_f32_32x32x16_f16 v[34:49], v[214:217], v[230:233], v[34:49]
	s_waitcnt vmcnt(6)
	ds_write_b128 v196, v[150:153] offset:25600
	s_waitcnt lgkmcnt(4)
	v_mfma_f32_32x32x16_f16 v[18:33], v[218:221], v[226:229], v[18:33]
	v_mfma_f32_32x32x16_f16 v[2:17], v[218:221], v[230:233], v[2:17]
	s_waitcnt lgkmcnt(0)
	s_barrier
	s_add_i32 s30, s30, 1
	s_cmp_lt_u32 s30, 15
	s_cbranch_scc1 .Lgp1_loop
;   __device__ __forceinline__ half_t* u() const { return (half_t*)(ws() + OFF_u); }
; template <class LA, class LB, class EP>
; __device__ __forceinline__ void gemm_tile_big(int K, LA loadA, LB loadB, EP epi, char* smem) {
;     ...
;   for (int kt = 0; kt < nk; ++kt) {
;     __syncthreads();
; #pragma unroll
;     for (int i = 0; i < 8; ++i) *(uint4*)&sA[(lr + 32 * i) * 72 + lc] = ra[i];
; #pragma unroll
;     for (int i = 0; i < 4; ++i) *(uint4*)&sB[(lr + 32 * i) * 72 + lc] = rb[i];
;     __syncthreads();
;     if (kt + 1 < nk) {
;       const int kk = (kt + 1) * 64 + lc;
; #pragma unroll
;       for (int i = 0; i < 8; ++i) ra[i] = loadA(lr + 32 * i, kk);
; #pragma unroll
;       for (int i = 0; i < 4; ++i) rb[i] = loadB(lr + 32 * i, kk);
;     }
; #pragma unroll
;     for (int s = 0; s < 4; ++s) {
;       h8 af[4], bf[2];
; #pragma unroll
;       for (int mi = 0; mi < 4; ++mi)
;         af[mi] = *(const h8*)&sA[(wm * 128 + mi * 32 + (lane & 31)) * 72 + s * 16 + (lane >> 5) * 8];
; #pragma unroll
;       for (int ni = 0; ni < 2; ++ni)
;         bf[ni] = *(const h8*)&sB[(wn * 64 + ni * 32 + (lane & 31)) * 72 + s * 16 + (lane >> 5) * 8];
; #pragma unroll
;       for (int mi = 0; mi < 4; ++mi)
; #pragma unroll
;         for (int ni = 0; ni < 2; ++ni)
;           acc[mi][ni] = __builtin_amdgcn_mfma_f32_32x32x16_f16(af[mi], bf[ni], acc[mi][ni], 0, 0, 0);
;     }
;   }
; __device__ __forceinline__ void phase_inproj(const KP& p, int l, char* smem, int* q, int xcc) {
;     ...
;         [&](int mi, int ni, int r, int row, int col, float v) {
;           const half_t hv = (half_t)(v + bv[ni]);
;           const int tok = m0 + row;
;           p.u()[(size_t)tok * NU + n0 + col] = hv;
	ds_read_b128 v[238:241], v179 offset:20480
	ds_read_b128 v[242:245], v179 offset:23040
	ds_read_b128 v[200:203], v178
	ds_read_b128 v[204:207], v178 offset:2560
	ds_read_b128 v[214:217], v178 offset:5120
	ds_read_b128 v[218:221], v178 offset:7680
	ds_read_b128 v[226:229], v179 offset:20512
	ds_read_b128 v[230:233], v179 offset:23072
	s_waitcnt lgkmcnt(5)
	v_mfma_f32_32x32x16_f16 v[114:129], v[200:203], v[238:241], v[114:129]
	v_mfma_f32_32x32x16_f16 v[98:113], v[200:203], v[242:245], v[98:113]
	ds_read_b128 v[200:203], v178 offset:32
	s_waitcnt lgkmcnt(5)
	v_mfma_f32_32x32x16_f16 v[82:97], v[204:207], v[238:241], v[82:97]
	v_mfma_f32_32x32x16_f16 v[66:81], v[204:207], v[242:245], v[66:81]
	ds_read_b128 v[204:207], v178 offset:2592
	s_waitcnt vmcnt(5)
	ds_write_b128 v196, v[154:157] offset:30720
	s_waitcnt lgkmcnt(6)
	v_mfma_f32_32x32x16_f16 v[50:65], v[214:217], v[238:241], v[50:65]
	v_mfma_f32_32x32x16_f16 v[34:49], v[214:217], v[242:245], v[34:49]
	ds_read_b128 v[214:217], v178 offset:5152
	s_waitcnt vmcnt(4)
	ds_write_b128 v196, v[158:161] offset:35840
	s_waitcnt lgkmcnt(7)
	v_mfma_f32_32x32x16_f16 v[18:33], v[218:221], v[238:241], v[18:33]
	v_mfma_f32_32x32x16_f16 v[2:17], v[218:221], v[242:245], v[2:17]
	ds_read_b128 v[218:221], v178 offset:7712
	s_waitcnt vmcnt(3)
	ds_write_b128 v196, v[162:165] offset:40960
	s_waitcnt lgkmcnt(6)
	v_mfma_f32_32x32x16_f16 v[114:129], v[200:203], v[226:229], v[114:129]
	v_mfma_f32_32x32x16_f16 v[98:113], v[200:203], v[230:233], v[98:113]
	s_waitcnt vmcnt(2)
	ds_write_b128 v196, v[166:169] offset:46080
	s_waitcnt lgkmcnt(6)
	v_mfma_f32_32x32x16_f16 v[82:97], v[204:207], v[226:229], v[82:97]
	v_mfma_f32_32x32x16_f16 v[66:81], v[204:207], v[230:233], v[66:81]
	s_waitcnt vmcnt(1)
	ds_write_b128 v196, v[170:173] offset:51200
	s_waitcnt lgkmcnt(5)
	v_mfma_f32_32x32x16_f16 v[50:65], v[214:217], v[226:229], v[50:65]
	v_mfma_f32_32x32x16_f16 v[34:49], v[214:217], v[230:233], v[34:49]
	s_waitcnt vmcnt(0)
	ds_write_b128 v196, v[174:177] offset:56320
	s_waitcnt lgkmcnt(4)
	v_mfma_f32_32x32x16_f16 v[18:33], v[218:221], v[226:229], v[18:33]
	v_mfma_f32_32x32x16_f16 v[2:17], v[218:221], v[230:233], v[2:17]
	s_waitcnt lgkmcnt(0)
	s_barrier
	ds_read_b128 v[238:241], v179 offset:51200
	ds_read_b128 v[242:245], v179 offset:53760
	ds_read_b128 v[200:203], v178 offset:30720
	ds_read_b128 v[204:207], v178 offset:33280
	ds_read_b128 v[214:217], v178 offset:35840
	ds_read_b128 v[218:221], v178 offset:38400
	ds_read_b128 v[226:229], v179 offset:51232
	ds_read_b128 v[230:233], v179 offset:53792
	s_waitcnt lgkmcnt(5)
	v_mfma_f32_32x32x16_f16 v[114:129], v[200:203], v[238:241], v[114:129]
	v_mfma_f32_32x32x16_f16 v[98:113], v[200:203], v[242:245], v[98:113]
	ds_read_b128 v[200:203], v178 offset:30752
	s_waitcnt lgkmcnt(5)
	v_mfma_f32_32x32x16_f16 v[82:97], v[204:207], v[238:241], v[82:97]
	v_mfma_f32_32x32x16_f16 v[66:81], v[204:207], v[242:245], v[66:81]
	ds_read_b128 v[204:207], v178 offset:33312
	s_waitcnt lgkmcnt(5)
	v_mfma_f32_32x32x16_f16 v[50:65], v[214:217], v[238:241], v[50:65]
	v_mfma_f32_32x32x16_f16 v[34:49], v[214:217], v[242:245], v[34:49]
	ds_read_b128 v[214:217], v178 offset:35872
	s_waitcnt lgkmcnt(5)
	v_mfma_f32_32x32x16_f16 v[18:33], v[218:221], v[238:241], v[18:33]
	v_mfma_f32_32x32x16_f16 v[2:17], v[218:221], v[242:245], v[2:17]
	ds_read_b128 v[218:221], v178 offset:38432
	s_waitcnt lgkmcnt(3)
	v_mfma_f32_32x32x16_f16 v[114:129], v[200:203], v[226:229], v[114:129]
	v_mfma_f32_32x32x16_f16 v[98:113], v[200:203], v[230:233], v[98:113]
	s_waitcnt lgkmcnt(2)
	v_mfma_f32_32x32x16_f16 v[82:97], v[204:207], v[226:229], v[82:97]
	v_mfma_f32_32x32x16_f16 v[66:81], v[204:207], v[230:233], v[66:81]
	s_waitcnt lgkmcnt(1)
	v_mfma_f32_32x32x16_f16 v[50:65], v[214:217], v[226:229], v[50:65]
	v_mfma_f32_32x32x16_f16 v[34:49], v[214:217], v[230:233], v[34:49]
	s_waitcnt lgkmcnt(0)
	v_mfma_f32_32x32x16_f16 v[18:33], v[218:221], v[226:229], v[18:33]
	v_mfma_f32_32x32x16_f16 v[2:17], v[218:221], v[230:233], v[2:17]
	s_waitcnt lgkmcnt(0)
	v_mov_b32_e32 v226, 1
	v_mov_b32_e32 v227, 0x11fe0
	v_mov_b32_e32 v228, 0x11fe4
	v_mov_b32_e32 v229, 0x100
	v_mov_b32_e32 v230, 2
	v_mov_b32_e32 v231, 0x3727c5ac
	v_mov_b32_e32 v232, 0x11fa0
	v_mov_b32_e32 v233, 0x80000
	v_mov_b32_e32 v238, 0x4000
	v_mov_b32_e32 v239, 0x4400
	v_mov_b32_e32 v240, 0x4800
	v_mov_b32_e32 v241, 0x4c00
	v_mov_b32_e32 v242, 0xf149f2ca
	v_mov_b32_e32 v243, 0x200
	v_mov_b32_e32 v244, 0x400
	v_mov_b32_e32 v245, 0x600
	s_nop 15
	s_lshl_b32 s14, s14, 8
	s_lshl_b64 s[2:3], s[18:19], 1
	s_add_u32 s18, s47, s2
	s_addc_u32 s19, s48, s3
	s_mul_i32 s2, s14, 0x3a00
	s_add_u32 s18, s18, s2
	s_addc_u32 s19, s19, 0
	v_lshrrev_b32_e32 v130, 7, v224
	v_lshlrev_b32_e32 v130, 5, v130
	v_bfe_u32 v131, v224, 5, 1
	v_add_u32_e32 v130, v130, v131
	v_mul_u32_u24_e32 v132, 0xe800, v130
	v_bfe_u32 v131, v224, 6, 1
	v_and_b32_e32 v133, 31, v224
	v_lshl_or_b32 v134, v131, 6, v133
	v_lshl_add_u32 v132, v134, 1, v132
	v_add_f32_e32 v114, v246, v114
	v_cvt_f16_f32_e32 v114, v114
	v_add_f32_e32 v115, v246, v115
	v_cvt_f16_f32_e32 v115, v115
	v_add_f32_e32 v116, v246, v116
	v_cvt_f16_f32_e32 v116, v116
	v_add_f32_e32 v117, v246, v117
	v_cvt_f16_f32_e32 v117, v117
	v_add_f32_e32 v118, v246, v118
	v_cvt_f16_f32_e32 v118, v118
	v_add_f32_e32 v119, v246, v119
	v_cvt_f16_f32_e32 v119, v119
	v_add_f32_e32 v120, v246, v120
	v_cvt_f16_f32_e32 v120, v120
	v_add_f32_e32 v121, v246, v121
	v_cvt_f16_f32_e32 v121, v121
	v_add_f32_e32 v122, v246, v122
	v_cvt_f16_f32_e32 v122, v122
	v_add_f32_e32 v123, v246, v123
	v_cvt_f16_f32_e32 v123, v123
	v_add_f32_e32 v124, v246, v124
	v_cvt_f16_f32_e32 v124, v124
; __device__ __forceinline__ void phase_inproj(const KP& p, int l, char* smem, int* q, int xcc) {
;     ...
;         [&](int mi, int ni, int r, int row, int col, float v) {
;           const half_t hv = (half_t)(v + bv[ni]);
	v_add_f32_e32 v125, v246, v125
	v_cvt_f16_f32_e32 v125, v125
	v_add_f32_e32 v126, v246, v126
	v_cvt_f16_f32_e32 v126, v126
	v_add_f32_e32 v127, v246, v127
	v_cvt_f16_f32_e32 v127, v127
	v_add_f32_e32 v128, v246, v128
	v_cvt_f16_f32_e32 v128, v128
	v_add_f32_e32 v129, v246, v129
	v_cvt_f16_f32_e32 v129, v129
	v_add_f32_e32 v98, v187, v98
	v_cvt_f16_f32_e32 v98, v98
	v_add_f32_e32 v99, v187, v99
	v_cvt_f16_f32_e32 v99, v99
	v_add_f32_e32 v100, v187, v100
	v_cvt_f16_f32_e32 v100, v100
	v_add_f32_e32 v101, v187, v101
	v_cvt_f16_f32_e32 v101, v101
	v_add_f32_e32 v102, v187, v102
	v_cvt_f16_f32_e32 v102, v102
	v_add_f32_e32 v103, v187, v103
	v_cvt_f16_f32_e32 v103, v103
	v_add_f32_e32 v104, v187, v104
	v_cvt_f16_f32_e32 v104, v104
	v_add_f32_e32 v105, v187, v105
	v_cvt_f16_f32_e32 v105, v105
	v_add_f32_e32 v106, v187, v106
	v_cvt_f16_f32_e32 v106, v106
	v_add_f32_e32 v107, v187, v107
	v_cvt_f16_f32_e32 v107, v107
	v_add_f32_e32 v108, v187, v108
	v_cvt_f16_f32_e32 v108, v108
	v_add_f32_e32 v109, v187, v109
	v_cvt_f16_f32_e32 v109, v109
	v_add_f32_e32 v110, v187, v110
	v_cvt_f16_f32_e32 v110, v110
	v_add_f32_e32 v111, v187, v111
	v_cvt_f16_f32_e32 v111, v111
	v_add_f32_e32 v112, v187, v112
	v_cvt_f16_f32_e32 v112, v112
	v_add_f32_e32 v113, v187, v113
	v_cvt_f16_f32_e32 v113, v113
	v_add_f32_e32 v82, v246, v82
	v_cvt_f16_f32_e32 v82, v82
	v_add_f32_e32 v83, v246, v83
	v_cvt_f16_f32_e32 v83, v83
	v_add_f32_e32 v84, v246, v84
	v_cvt_f16_f32_e32 v84, v84
	v_add_f32_e32 v85, v246, v85
	v_cvt_f16_f32_e32 v85, v85
	v_add_f32_e32 v86, v246, v86
	v_cvt_f16_f32_e32 v86, v86
	v_add_f32_e32 v87, v246, v87
	v_cvt_f16_f32_e32 v87, v87
	v_add_f32_e32 v88, v246, v88
	v_cvt_f16_f32_e32 v88, v88
	v_add_f32_e32 v89, v246, v89
	v_cvt_f16_f32_e32 v89, v89
	v_add_f32_e32 v90, v246, v90
	v_cvt_f16_f32_e32 v90, v90
	v_add_f32_e32 v91, v246, v91
	v_cvt_f16_f32_e32 v91, v91
	v_add_f32_e32 v92, v246, v92
	v_cvt_f16_f32_e32 v92, v92
	v_add_f32_e32 v93, v246, v93
	v_cvt_f16_f32_e32 v93, v93
	v_add_f32_e32 v94, v246, v94
	v_cvt_f16_f32_e32 v94, v94
	v_add_f32_e32 v95, v246, v95
	v_cvt_f16_f32_e32 v95, v95
	v_add_f32_e32 v96, v246, v96
	v_cvt_f16_f32_e32 v96, v96
	v_add_f32_e32 v97, v246, v97
	v_cvt_f16_f32_e32 v97, v97
	v_add_f32_e32 v66, v187, v66
	v_cvt_f16_f32_e32 v66, v66
	v_add_f32_e32 v67, v187, v67
	v_cvt_f16_f32_e32 v67, v67
	v_add_f32_e32 v68, v187, v68
	v_cvt_f16_f32_e32 v68, v68
	v_add_f32_e32 v69, v187, v69
	v_cvt_f16_f32_e32 v69, v69
	v_add_f32_e32 v70, v187, v70
	v_cvt_f16_f32_e32 v70, v70
	v_add_f32_e32 v71, v187, v71
	v_cvt_f16_f32_e32 v71, v71
	v_add_f32_e32 v72, v187, v72
	v_cvt_f16_f32_e32 v72, v72
	v_add_f32_e32 v73, v187, v73
	v_cvt_f16_f32_e32 v73, v73
	v_add_f32_e32 v74, v187, v74
	v_cvt_f16_f32_e32 v74, v74
	v_add_f32_e32 v75, v187, v75
	v_cvt_f16_f32_e32 v75, v75
	v_add_f32_e32 v76, v187, v76
	v_cvt_f16_f32_e32 v76, v76
	v_add_f32_e32 v77, v187, v77
	v_cvt_f16_f32_e32 v77, v77
	v_add_f32_e32 v78, v187, v78
	v_cvt_f16_f32_e32 v78, v78
	v_add_f32_e32 v79, v187, v79
	v_cvt_f16_f32_e32 v79, v79
	v_add_f32_e32 v80, v187, v80
	v_cvt_f16_f32_e32 v80, v80
	v_add_f32_e32 v81, v187, v81
	v_cvt_f16_f32_e32 v81, v81
	v_add_f32_e32 v50, v246, v50
	v_cvt_f16_f32_e32 v50, v50
	v_add_f32_e32 v51, v246, v51
	v_cvt_f16_f32_e32 v51, v51
	v_add_f32_e32 v52, v246, v52
	v_cvt_f16_f32_e32 v52, v52
	v_add_f32_e32 v53, v246, v53
	v_cvt_f16_f32_e32 v53, v53
	v_add_f32_e32 v54, v246, v54
	v_cvt_f16_f32_e32 v54, v54
	v_add_f32_e32 v55, v246, v55
	v_cvt_f16_f32_e32 v55, v55
	v_add_f32_e32 v56, v246, v56
	v_cvt_f16_f32_e32 v56, v56
	v_add_f32_e32 v57, v246, v57
	v_cvt_f16_f32_e32 v57, v57
	v_add_f32_e32 v58, v246, v58
	v_cvt_f16_f32_e32 v58, v58
	v_add_f32_e32 v59, v246, v59
	v_cvt_f16_f32_e32 v59, v59
	v_add_f32_e32 v60, v246, v60
	v_cvt_f16_f32_e32 v60, v60
	v_add_f32_e32 v61, v246, v61
	v_cvt_f16_f32_e32 v61, v61
	v_add_f32_e32 v62, v246, v62
	v_cvt_f16_f32_e32 v62, v62
	v_add_f32_e32 v63, v246, v63
	v_cvt_f16_f32_e32 v63, v63
	v_add_f32_e32 v64, v246, v64
	v_cvt_f16_f32_e32 v64, v64
	v_add_f32_e32 v65, v246, v65
	v_cvt_f16_f32_e32 v65, v65
	v_add_f32_e32 v34, v187, v34
	v_cvt_f16_f32_e32 v34, v34
	v_add_f32_e32 v35, v187, v35
	v_cvt_f16_f32_e32 v35, v35
	v_add_f32_e32 v36, v187, v36
	v_cvt_f16_f32_e32 v36, v36
	v_add_f32_e32 v37, v187, v37
	v_cvt_f16_f32_e32 v37, v37
	v_add_f32_e32 v38, v187, v38
	v_cvt_f16_f32_e32 v38, v38
	v_add_f32_e32 v39, v187, v39
	v_cvt_f16_f32_e32 v39, v39
	v_add_f32_e32 v40, v187, v40
	v_cvt_f16_f32_e32 v40, v40
	v_add_f32_e32 v41, v187, v41
	v_cvt_f16_f32_e32 v41, v41
	v_add_f32_e32 v42, v187, v42
	v_cvt_f16_f32_e32 v42, v42
	v_add_f32_e32 v43, v187, v43
	v_cvt_f16_f32_e32 v43, v43
	v_add_f32_e32 v44, v187, v44
	v_cvt_f16_f32_e32 v44, v44
	v_add_f32_e32 v45, v187, v45
	v_cvt_f16_f32_e32 v45, v45
	v_add_f32_e32 v46, v187, v46
	v_cvt_f16_f32_e32 v46, v46
	v_add_f32_e32 v47, v187, v47
	v_cvt_f16_f32_e32 v47, v47
	v_add_f32_e32 v48, v187, v48
	v_cvt_f16_f32_e32 v48, v48
	v_add_f32_e32 v49, v187, v49
	v_cvt_f16_f32_e32 v49, v49
	v_add_f32_e32 v18, v246, v18
	v_cvt_f16_f32_e32 v18, v18
	v_add_f32_e32 v19, v246, v19
	v_cvt_f16_f32_e32 v19, v19
	v_add_f32_e32 v20, v246, v20
	v_cvt_f16_f32_e32 v20, v20
	v_add_f32_e32 v21, v246, v21
	v_cvt_f16_f32_e32 v21, v21
	v_add_f32_e32 v22, v246, v22
	v_cvt_f16_f32_e32 v22, v22
	v_add_f32_e32 v23, v246, v23
	v_cvt_f16_f32_e32 v23, v23
	v_add_f32_e32 v24, v246, v24
	v_cvt_f16_f32_e32 v24, v24
	v_add_f32_e32 v25, v246, v25
	v_cvt_f16_f32_e32 v25, v25
	v_add_f32_e32 v26, v246, v26
	v_cvt_f16_f32_e32 v26, v26
	v_add_f32_e32 v27, v246, v27
	v_cvt_f16_f32_e32 v27, v27
	v_add_f32_e32 v28, v246, v28
	v_cvt_f16_f32_e32 v28, v28
;   __device__ __forceinline__ half_t* u() const { return (half_t*)(ws() + OFF_u); }
; __device__ __forceinline__ void phase_inproj(const KP& p, int l, char* smem, int* q, int xcc) {
;     ...
;         [&](int mi, int ni, int r, int row, int col, float v) {
;           const half_t hv = (half_t)(v + bv[ni]);
;           const int tok = m0 + row;
;           p.u()[(size_t)tok * NU + n0 + col] = hv;
	v_add_f32_e32 v29, v246, v29
	v_cvt_f16_f32_e32 v29, v29
	v_add_f32_e32 v30, v246, v30
	v_cvt_f16_f32_e32 v30, v30
	v_add_f32_e32 v31, v246, v31
	v_cvt_f16_f32_e32 v31, v31
	v_add_f32_e32 v32, v246, v32
	v_cvt_f16_f32_e32 v32, v32
	v_add_f32_e32 v33, v246, v33
	v_cvt_f16_f32_e32 v33, v33
	v_add_f32_e32 v2, v187, v2
	v_cvt_f16_f32_e32 v2, v2
	v_add_f32_e32 v3, v187, v3
	v_cvt_f16_f32_e32 v3, v3
	v_add_f32_e32 v4, v187, v4
	v_cvt_f16_f32_e32 v4, v4
	v_add_f32_e32 v5, v187, v5
	v_cvt_f16_f32_e32 v5, v5
	v_add_f32_e32 v6, v187, v6
	v_cvt_f16_f32_e32 v6, v6
	v_add_f32_e32 v7, v187, v7
	v_cvt_f16_f32_e32 v7, v7
	v_add_f32_e32 v8, v187, v8
	v_cvt_f16_f32_e32 v8, v8
	v_add_f32_e32 v9, v187, v9
	v_cvt_f16_f32_e32 v9, v9
	v_add_f32_e32 v10, v187, v10
	v_cvt_f16_f32_e32 v10, v10
	v_add_f32_e32 v11, v187, v11
	v_cvt_f16_f32_e32 v11, v11
	v_add_f32_e32 v12, v187, v12
	v_cvt_f16_f32_e32 v12, v12
	v_add_f32_e32 v13, v187, v13
	v_cvt_f16_f32_e32 v13, v13
	v_add_f32_e32 v14, v187, v14
	v_cvt_f16_f32_e32 v14, v14
	v_add_f32_e32 v15, v187, v15
	v_cvt_f16_f32_e32 v15, v15
	v_add_f32_e32 v16, v187, v16
	v_cvt_f16_f32_e32 v16, v16
	v_add_f32_e32 v17, v187, v17
	v_cvt_f16_f32_e32 v17, v17
	s_add_u32 s2, s18, 0x0
	s_addc_u32 s3, s19, 0
	global_store_short v132, v114, s[2:3]
	global_store_short v132, v98, s[2:3] offset:64
	s_add_u32 s2, s18, 0x3a00
	s_addc_u32 s3, s19, 0
	global_store_short v132, v115, s[2:3]
	global_store_short v132, v99, s[2:3] offset:64
	s_add_u32 s2, s18, 0x7400
	s_addc_u32 s3, s19, 0
	global_store_short v132, v116, s[2:3]
	global_store_short v132, v100, s[2:3] offset:64
	s_add_u32 s2, s18, 0xae00
	s_addc_u32 s3, s19, 0
	global_store_short v132, v117, s[2:3]
	global_store_short v132, v101, s[2:3] offset:64
	s_add_u32 s2, s18, 0x1d000
	s_addc_u32 s3, s19, 0
	global_store_short v132, v118, s[2:3]
	global_store_short v132, v102, s[2:3] offset:64
	s_add_u32 s2, s18, 0x20a00
	s_addc_u32 s3, s19, 0
	global_store_short v132, v119, s[2:3]
	global_store_short v132, v103, s[2:3] offset:64
	s_add_u32 s2, s18, 0x24400
	s_addc_u32 s3, s19, 0
	global_store_short v132, v120, s[2:3]
	global_store_short v132, v104, s[2:3] offset:64
	s_add_u32 s2, s18, 0x27e00
	s_addc_u32 s3, s19, 0
	global_store_short v132, v121, s[2:3]
	global_store_short v132, v105, s[2:3] offset:64
	s_add_u32 s2, s18, 0x3a000
	s_addc_u32 s3, s19, 0
	global_store_short v132, v122, s[2:3]
	global_store_short v132, v106, s[2:3] offset:64
	s_add_u32 s2, s18, 0x3da00
	s_addc_u32 s3, s19, 0
	global_store_short v132, v123, s[2:3]
	global_store_short v132, v107, s[2:3] offset:64
	s_add_u32 s2, s18, 0x41400
	s_addc_u32 s3, s19, 0
	global_store_short v132, v124, s[2:3]
	global_store_short v132, v108, s[2:3] offset:64
	s_add_u32 s2, s18, 0x44e00
	s_addc_u32 s3, s19, 0
	global_store_short v132, v125, s[2:3]
	global_store_short v132, v109, s[2:3] offset:64
	s_add_u32 s2, s18, 0x57000
	s_addc_u32 s3, s19, 0
	global_store_short v132, v126, s[2:3]
	global_store_short v132, v110, s[2:3] offset:64
	s_add_u32 s2, s18, 0x5aa00
	s_addc_u32 s3, s19, 0
	global_store_short v132, v127, s[2:3]
	global_store_short v132, v111, s[2:3] offset:64
	s_add_u32 s2, s18, 0x5e400
	s_addc_u32 s3, s19, 0
	global_store_short v132, v128, s[2:3]
	global_store_short v132, v112, s[2:3] offset:64
	s_add_u32 s2, s18, 0x61e00
	s_addc_u32 s3, s19, 0
	global_store_short v132, v129, s[2:3]
	global_store_short v132, v113, s[2:3] offset:64
	s_add_u32 s2, s18, 0x74000
	s_addc_u32 s3, s19, 0
	global_store_short v132, v82, s[2:3]
	global_store_short v132, v66, s[2:3] offset:64
	s_add_u32 s2, s18, 0x77a00
	s_addc_u32 s3, s19, 0
	global_store_short v132, v83, s[2:3]
	global_store_short v132, v67, s[2:3] offset:64
	s_add_u32 s2, s18, 0x7b400
	s_addc_u32 s3, s19, 0
	global_store_short v132, v84, s[2:3]
	global_store_short v132, v68, s[2:3] offset:64
	s_add_u32 s2, s18, 0x7ee00
	s_addc_u32 s3, s19, 0
	global_store_short v132, v85, s[2:3]
	global_store_short v132, v69, s[2:3] offset:64
	s_add_u32 s2, s18, 0x91000
	s_addc_u32 s3, s19, 0
	global_store_short v132, v86, s[2:3]
	global_store_short v132, v70, s[2:3] offset:64
	s_add_u32 s2, s18, 0x94a00
	s_addc_u32 s3, s19, 0
	global_store_short v132, v87, s[2:3]
	global_store_short v132, v71, s[2:3] offset:64
	s_add_u32 s2, s18, 0x98400
	s_addc_u32 s3, s19, 0
	global_store_short v132, v88, s[2:3]
	global_store_short v132, v72, s[2:3] offset:64
	s_add_u32 s2, s18, 0x9be00
	s_addc_u32 s3, s19, 0
	global_store_short v132, v89, s[2:3]
	global_store_short v132, v73, s[2:3] offset:64
	s_add_u32 s2, s18, 0xae000
	s_addc_u32 s3, s19, 0
	global_store_short v132, v90, s[2:3]
	global_store_short v132, v74, s[2:3] offset:64
	s_add_u32 s2, s18, 0xb1a00
	s_addc_u32 s3, s19, 0
	global_store_short v132, v91, s[2:3]
	global_store_short v132, v75, s[2:3] offset:64
	s_add_u32 s2, s18, 0xb5400
	s_addc_u32 s3, s19, 0
	global_store_short v132, v92, s[2:3]
	global_store_short v132, v76, s[2:3] offset:64
	s_add_u32 s2, s18, 0xb8e00
	s_addc_u32 s3, s19, 0
	global_store_short v132, v93, s[2:3]
	global_store_short v132, v77, s[2:3] offset:64
	s_add_u32 s2, s18, 0xcb000
	s_addc_u32 s3, s19, 0
	global_store_short v132, v94, s[2:3]
	global_store_short v132, v78, s[2:3] offset:64
	s_add_u32 s2, s18, 0xcea00
	s_addc_u32 s3, s19, 0
	global_store_short v132, v95, s[2:3]
	global_store_short v132, v79, s[2:3] offset:64
	s_add_u32 s2, s18, 0xd2400
	s_addc_u32 s3, s19, 0
	global_store_short v132, v96, s[2:3]
	global_store_short v132, v80, s[2:3] offset:64
	s_add_u32 s2, s18, 0xd5e00
	s_addc_u32 s3, s19, 0
	global_store_short v132, v97, s[2:3]
	global_store_short v132, v81, s[2:3] offset:64
	s_add_u32 s2, s18, 0xe8000
	s_addc_u32 s3, s19, 0
;   __device__ __forceinline__ half_t* u() const { return (half_t*)(ws() + OFF_u); }
; __device__ __forceinline__ void phase_inproj(const KP& p, int l, char* smem, int* q, int xcc) {
;     ...
;         [&](int mi, int ni, int r, int row, int col, float v) {
;           const half_t hv = (half_t)(v + bv[ni]);
;           const int tok = m0 + row;
;           p.u()[(size_t)tok * NU + n0 + col] = hv;
;           if (vT) {
	global_store_short v132, v50, s[2:3]
	global_store_short v132, v34, s[2:3] offset:64
	s_add_u32 s2, s18, 0xeba00
	s_addc_u32 s3, s19, 0
	global_store_short v132, v51, s[2:3]
	global_store_short v132, v35, s[2:3] offset:64
	s_add_u32 s2, s18, 0xef400
	s_addc_u32 s3, s19, 0
	global_store_short v132, v52, s[2:3]
	global_store_short v132, v36, s[2:3] offset:64
	s_add_u32 s2, s18, 0xf2e00
	s_addc_u32 s3, s19, 0
	global_store_short v132, v53, s[2:3]
	global_store_short v132, v37, s[2:3] offset:64
	s_add_u32 s2, s18, 0x105000
	s_addc_u32 s3, s19, 0
	global_store_short v132, v54, s[2:3]
	global_store_short v132, v38, s[2:3] offset:64
	s_add_u32 s2, s18, 0x108a00
	s_addc_u32 s3, s19, 0
	global_store_short v132, v55, s[2:3]
	global_store_short v132, v39, s[2:3] offset:64
	s_add_u32 s2, s18, 0x10c400
	s_addc_u32 s3, s19, 0
	global_store_short v132, v56, s[2:3]
	global_store_short v132, v40, s[2:3] offset:64
	s_add_u32 s2, s18, 0x10fe00
	s_addc_u32 s3, s19, 0
	global_store_short v132, v57, s[2:3]
	global_store_short v132, v41, s[2:3] offset:64
	s_add_u32 s2, s18, 0x122000
	s_addc_u32 s3, s19, 0
	global_store_short v132, v58, s[2:3]
	global_store_short v132, v42, s[2:3] offset:64
	s_add_u32 s2, s18, 0x125a00
	s_addc_u32 s3, s19, 0
	global_store_short v132, v59, s[2:3]
	global_store_short v132, v43, s[2:3] offset:64
	s_add_u32 s2, s18, 0x129400
	s_addc_u32 s3, s19, 0
	global_store_short v132, v60, s[2:3]
	global_store_short v132, v44, s[2:3] offset:64
	s_add_u32 s2, s18, 0x12ce00
	s_addc_u32 s3, s19, 0
	global_store_short v132, v61, s[2:3]
	global_store_short v132, v45, s[2:3] offset:64
	s_add_u32 s2, s18, 0x13f000
	s_addc_u32 s3, s19, 0
	global_store_short v132, v62, s[2:3]
	global_store_short v132, v46, s[2:3] offset:64
	s_add_u32 s2, s18, 0x142a00
	s_addc_u32 s3, s19, 0
	global_store_short v132, v63, s[2:3]
	global_store_short v132, v47, s[2:3] offset:64
	s_add_u32 s2, s18, 0x146400
	s_addc_u32 s3, s19, 0
	global_store_short v132, v64, s[2:3]
	global_store_short v132, v48, s[2:3] offset:64
	s_add_u32 s2, s18, 0x149e00
	s_addc_u32 s3, s19, 0
	global_store_short v132, v65, s[2:3]
	global_store_short v132, v49, s[2:3] offset:64
	s_add_u32 s2, s18, 0x15c000
	s_addc_u32 s3, s19, 0
	global_store_short v132, v18, s[2:3]
	global_store_short v132, v2, s[2:3] offset:64
	s_add_u32 s2, s18, 0x15fa00
	s_addc_u32 s3, s19, 0
	global_store_short v132, v19, s[2:3]
	global_store_short v132, v3, s[2:3] offset:64
	s_add_u32 s2, s18, 0x163400
	s_addc_u32 s3, s19, 0
	global_store_short v132, v20, s[2:3]
	global_store_short v132, v4, s[2:3] offset:64
	s_add_u32 s2, s18, 0x166e00
	s_addc_u32 s3, s19, 0
	global_store_short v132, v21, s[2:3]
	global_store_short v132, v5, s[2:3] offset:64
	s_add_u32 s2, s18, 0x179000
	s_addc_u32 s3, s19, 0
	global_store_short v132, v22, s[2:3]
	global_store_short v132, v6, s[2:3] offset:64
	s_add_u32 s2, s18, 0x17ca00
	s_addc_u32 s3, s19, 0
	global_store_short v132, v23, s[2:3]
	global_store_short v132, v7, s[2:3] offset:64
	s_add_u32 s2, s18, 0x180400
	s_addc_u32 s3, s19, 0
	global_store_short v132, v24, s[2:3]
	global_store_short v132, v8, s[2:3] offset:64
	s_add_u32 s2, s18, 0x183e00
	s_addc_u32 s3, s19, 0
	global_store_short v132, v25, s[2:3]
	global_store_short v132, v9, s[2:3] offset:64
	s_add_u32 s2, s18, 0x196000
	s_addc_u32 s3, s19, 0
	global_store_short v132, v26, s[2:3]
	global_store_short v132, v10, s[2:3] offset:64
	s_add_u32 s2, s18, 0x199a00
	s_addc_u32 s3, s19, 0
	global_store_short v132, v27, s[2:3]
	global_store_short v132, v11, s[2:3] offset:64
	s_add_u32 s2, s18, 0x19d400
	s_addc_u32 s3, s19, 0
	global_store_short v132, v28, s[2:3]
	global_store_short v132, v12, s[2:3] offset:64
	s_add_u32 s2, s18, 0x1a0e00
	s_addc_u32 s3, s19, 0
	global_store_short v132, v29, s[2:3]
	global_store_short v132, v13, s[2:3] offset:64
	s_add_u32 s2, s18, 0x1b3000
	s_addc_u32 s3, s19, 0
	global_store_short v132, v30, s[2:3]
	global_store_short v132, v14, s[2:3] offset:64
	s_add_u32 s2, s18, 0x1b6a00
	s_addc_u32 s3, s19, 0
	global_store_short v132, v31, s[2:3]
	global_store_short v132, v15, s[2:3] offset:64
	s_add_u32 s2, s18, 0x1ba400
	s_addc_u32 s3, s19, 0
	global_store_short v132, v32, s[2:3]
	global_store_short v132, v16, s[2:3] offset:64
	s_add_u32 s2, s18, 0x1bde00
	s_addc_u32 s3, s19, 0
	global_store_short v132, v33, s[2:3]
	global_store_short v132, v17, s[2:3] offset:64
	s_cmp_lg_u64 s[40:41], 0
	s_cbranch_scc0 .Lip_novt
; __device__ __forceinline__ void phase_inproj(const KP& p, int l, char* smem, int* q, int xcc) {
;     ...
;           if (vT) {
;             const int b = tok >> 13, t = tok & 8191;
;             vT[((size_t)(b * 2 + (col >> 6)) * 64 + (col & 63)) * SEQ + t] = hv;
;           }
	s_lshr_b32 s2, s14, 13
	s_lshl_b32 s2, s2, 21
	s_and_b32 s3, s14, 0x1fff
	s_lshl_b32 s3, s3, 1
	s_add_u32 s2, s2, s3
	s_add_u32 s40, s40, s2
	s_addc_u32 s41, s41, 0
	v_lshlrev_b32_e32 v135, 14, v134
	v_lshl_add_u32 v135, v130, 3, v135
	v_pack_b32_f16 v136, v114, v115
	v_pack_b32_f16 v137, v116, v117
	s_add_u32 s2, s40, 0x0
	s_addc_u32 s3, s41, 0
	global_store_dwordx2 v135, v[136:137], s[2:3]
	v_pack_b32_f16 v138, v118, v119
	v_pack_b32_f16 v139, v120, v121
	s_add_u32 s2, s40, 0x10
	s_addc_u32 s3, s41, 0
	global_store_dwordx2 v135, v[138:139], s[2:3]
	v_pack_b32_f16 v140, v122, v123
	v_pack_b32_f16 v141, v124, v125
	s_add_u32 s2, s40, 0x20
	s_addc_u32 s3, s41, 0
	global_store_dwordx2 v135, v[140:141], s[2:3]
	v_pack_b32_f16 v142, v126, v127
	v_pack_b32_f16 v143, v128, v129
	s_add_u32 s2, s40, 0x30
	s_addc_u32 s3, s41, 0
	global_store_dwordx2 v135, v[142:143], s[2:3]
	v_pack_b32_f16 v136, v98, v99
	v_pack_b32_f16 v137, v100, v101
	s_add_u32 s2, s40, 0x80000
	s_addc_u32 s3, s41, 0
	global_store_dwordx2 v135, v[136:137], s[2:3]
	v_pack_b32_f16 v138, v102, v103
	v_pack_b32_f16 v139, v104, v105
	s_add_u32 s2, s40, 0x80010
	s_addc_u32 s3, s41, 0
	global_store_dwordx2 v135, v[138:139], s[2:3]
	v_pack_b32_f16 v140, v106, v107
	v_pack_b32_f16 v141, v108, v109
	s_add_u32 s2, s40, 0x80020
	s_addc_u32 s3, s41, 0
	global_store_dwordx2 v135, v[140:141], s[2:3]
	v_pack_b32_f16 v142, v110, v111
	v_pack_b32_f16 v143, v112, v113
	s_add_u32 s2, s40, 0x80030
	s_addc_u32 s3, s41, 0
	global_store_dwordx2 v135, v[142:143], s[2:3]
	v_pack_b32_f16 v136, v82, v83
	v_pack_b32_f16 v137, v84, v85
	s_add_u32 s2, s40, 0x40
	s_addc_u32 s3, s41, 0
	global_store_dwordx2 v135, v[136:137], s[2:3]
	v_pack_b32_f16 v138, v86, v87
	v_pack_b32_f16 v139, v88, v89
	s_add_u32 s2, s40, 0x50
	s_addc_u32 s3, s41, 0
	global_store_dwordx2 v135, v[138:139], s[2:3]
	v_pack_b32_f16 v140, v90, v91
	v_pack_b32_f16 v141, v92, v93
	s_add_u32 s2, s40, 0x60
	s_addc_u32 s3, s41, 0
	global_store_dwordx2 v135, v[140:141], s[2:3]
	v_pack_b32_f16 v142, v94, v95
	v_pack_b32_f16 v143, v96, v97
	s_add_u32 s2, s40, 0x70
	s_addc_u32 s3, s41, 0
	global_store_dwordx2 v135, v[142:143], s[2:3]
	v_pack_b32_f16 v136, v66, v67
	v_pack_b32_f16 v137, v68, v69
	s_add_u32 s2, s40, 0x80040
	s_addc_u32 s3, s41, 0
	global_store_dwordx2 v135, v[136:137], s[2:3]
	v_pack_b32_f16 v138, v70, v71
	v_pack_b32_f16 v139, v72, v73
	s_add_u32 s2, s40, 0x80050
	s_addc_u32 s3, s41, 0
	global_store_dwordx2 v135, v[138:139], s[2:3]
	v_pack_b32_f16 v140, v74, v75
	v_pack_b32_f16 v141, v76, v77
	s_add_u32 s2, s40, 0x80060
	s_addc_u32 s3, s41, 0
	global_store_dwordx2 v135, v[140:141], s[2:3]
	v_pack_b32_f16 v142, v78, v79
	v_pack_b32_f16 v143, v80, v81
	s_add_u32 s2, s40, 0x80070
	s_addc_u32 s3, s41, 0
	global_store_dwordx2 v135, v[142:143], s[2:3]
	v_pack_b32_f16 v136, v50, v51
	v_pack_b32_f16 v137, v52, v53
	s_add_u32 s2, s40, 0x80
	s_addc_u32 s3, s41, 0
	global_store_dwordx2 v135, v[136:137], s[2:3]
	v_pack_b32_f16 v138, v54, v55
	v_pack_b32_f16 v139, v56, v57
	s_add_u32 s2, s40, 0x90
	s_addc_u32 s3, s41, 0
	global_store_dwordx2 v135, v[138:139], s[2:3]
	v_pack_b32_f16 v140, v58, v59
	v_pack_b32_f16 v141, v60, v61
	s_add_u32 s2, s40, 0xa0
	s_addc_u32 s3, s41, 0
	global_store_dwordx2 v135, v[140:141], s[2:3]
	v_pack_b32_f16 v142, v62, v63
	v_pack_b32_f16 v143, v64, v65
	s_add_u32 s2, s40, 0xb0
	s_addc_u32 s3, s41, 0
	global_store_dwordx2 v135, v[142:143], s[2:3]
	v_pack_b32_f16 v136, v34, v35
	v_pack_b32_f16 v137, v36, v37
	s_add_u32 s2, s40, 0x80080
	s_addc_u32 s3, s41, 0
	global_store_dwordx2 v135, v[136:137], s[2:3]
	v_pack_b32_f16 v138, v38, v39
	v_pack_b32_f16 v139, v40, v41
	s_add_u32 s2, s40, 0x80090
	s_addc_u32 s3, s41, 0
	global_store_dwordx2 v135, v[138:139], s[2:3]
	v_pack_b32_f16 v140, v42, v43
	v_pack_b32_f16 v141, v44, v45
	s_add_u32 s2, s40, 0x800a0
	s_addc_u32 s3, s41, 0
	global_store_dwordx2 v135, v[140:141], s[2:3]
	v_pack_b32_f16 v142, v46, v47
	v_pack_b32_f16 v143, v48, v49
	s_add_u32 s2, s40, 0x800b0
	s_addc_u32 s3, s41, 0
	global_store_dwordx2 v135, v[142:143], s[2:3]
	v_pack_b32_f16 v136, v18, v19
	v_pack_b32_f16 v137, v20, v21
	s_add_u32 s2, s40, 0xc0
	s_addc_u32 s3, s41, 0
	global_store_dwordx2 v135, v[136:137], s[2:3]
	v_pack_b32_f16 v138, v22, v23
	v_pack_b32_f16 v139, v24, v25
	s_add_u32 s2, s40, 0xd0
	s_addc_u32 s3, s41, 0
	global_store_dwordx2 v135, v[138:139], s[2:3]
	v_pack_b32_f16 v140, v26, v27
	v_pack_b32_f16 v141, v28, v29
	s_add_u32 s2, s40, 0xe0
	s_addc_u32 s3, s41, 0
	global_store_dwordx2 v135, v[140:141], s[2:3]
	v_pack_b32_f16 v142, v30, v31
	v_pack_b32_f16 v143, v32, v33
	s_add_u32 s2, s40, 0xf0
	s_addc_u32 s3, s41, 0
	global_store_dwordx2 v135, v[142:143], s[2:3]
	v_pack_b32_f16 v136, v2, v3
	v_pack_b32_f16 v137, v4, v5
	s_add_u32 s2, s40, 0x800c0
	s_addc_u32 s3, s41, 0
	global_store_dwordx2 v135, v[136:137], s[2:3]
	v_pack_b32_f16 v138, v6, v7
	v_pack_b32_f16 v139, v8, v9
	s_add_u32 s2, s40, 0x800d0
	s_addc_u32 s3, s41, 0
	global_store_dwordx2 v135, v[138:139], s[2:3]
	v_pack_b32_f16 v140, v10, v11
	v_pack_b32_f16 v141, v12, v13
	s_add_u32 s2, s40, 0x800e0
	s_addc_u32 s3, s41, 0
	global_store_dwordx2 v135, v[140:141], s[2:3]
	v_pack_b32_f16 v142, v14, v15
	v_pack_b32_f16 v143, v16, v17
	s_add_u32 s2, s40, 0x800f0
	s_addc_u32 s3, s41, 0
	global_store_dwordx2 v135, v[142:143], s[2:3]

; __device__ __forceinline__ void dsa_item(const KP& p, int b, int tile, char* smem) {
;     ...
; #pragma unroll
;         for (int i = 0; i < 8; ++i) {
;           const int pos = (g8 * 8 + i) * 8 + rs;
;           const f32x4 pa = *(const f32x4*)&pbuf[pos * 8];
;           const f32x4 pb = *(const f32x4*)&pbuf[pos * 8 + 4];
;           float vf[8];
; #pragma unroll
;           for (int e = 0; e < 8; ++e) vf[e] = (float)vv[i][e];
; #pragma unroll
;           for (int e = 0; e < 8; ++e) {
;             acc[0][e] += pa[0] * vf[e]; acc[1][e] += pa[1] * vf[e]; acc[2][e] += pa[2] * vf[e]; acc[3][e] += pa[3] * vf[e];
;             acc[4][e] += pb[0] * vf[e]; acc[5][e] += pb[1] * vf[e]; acc[6][e] += pb[2] * vf[e]; acc[7][e] += pb[3] * vf[e];
;           }
;         }
.LBB0_1512:
	s_waitcnt vmcnt(7)
	v_cvt_f32_f16_sdwa v175, v2 dst_sel:DWORD dst_unused:UNUSED_PAD src0_sel:WORD_1
	v_cvt_f32_f16_e32 v174, v2
	s_waitcnt vmcnt(6)
	v_cvt_f32_f16_sdwa v177, v6 dst_sel:DWORD dst_unused:UNUSED_PAD src0_sel:WORD_1
	v_cvt_f32_f16_e32 v176, v6
	ds_read_b128 v[58:61], v172
	ds_read_b128 v[34:37], v172 offset:16
	ds_read_b128 v[62:65], v172 offset:256
	ds_read_b128 v[38:41], v172 offset:272
	ds_read_b128 v[66:69], v172 offset:512
	ds_read_b128 v[42:45], v172 offset:528
	ds_read_b128 v[70:73], v172 offset:768
	ds_read_b128 v[46:49], v172 offset:784
	ds_read_b128 v[74:77], v172 offset:1024
	ds_read_b128 v[50:53], v172 offset:1040
	s_waitcnt vmcnt(5)
	v_cvt_f32_f16_sdwa v179, v10 dst_sel:DWORD dst_unused:UNUSED_PAD src0_sel:WORD_1
	v_cvt_f32_f16_e32 v178, v10
	s_waitcnt lgkmcnt(8)
	v_mov_b32_e32 v156, v37
	s_waitcnt vmcnt(4)
	v_cvt_f32_f16_sdwa v181, v14 dst_sel:DWORD dst_unused:UNUSED_PAD src0_sel:WORD_1
	v_cvt_f32_f16_e32 v180, v14
	v_pk_fma_f32 v[148:149], v[156:157], v[174:175], v[148:149] op_sel_hi:[0,1,1]
	s_waitcnt lgkmcnt(6)
	v_mov_b32_e32 v6, v41
	s_waitcnt vmcnt(3)
	v_cvt_f32_f16_sdwa v189, v22 dst_sel:DWORD dst_unused:UNUSED_PAD src0_sel:WORD_1
	v_cvt_f32_f16_e32 v188, v22
	v_pk_fma_f32 v[148:149], v[6:7], v[176:177], v[148:149] op_sel_hi:[0,1,1]
	s_waitcnt lgkmcnt(4)
	v_mov_b32_e32 v10, v45
	v_pk_fma_f32 v[148:149], v[10:11], v[178:179], v[148:149] op_sel_hi:[0,1,1]
	s_waitcnt lgkmcnt(2)
	v_mov_b32_e32 v22, v49
	v_pk_fma_f32 v[148:149], v[22:23], v[180:181], v[148:149] op_sel_hi:[0,1,1]
	s_waitcnt lgkmcnt(0)
	v_mov_b32_e32 v158, v53
	ds_read_b128 v[78:81], v172 offset:1280
	ds_read_b128 v[54:57], v172 offset:1296
	v_pk_fma_f32 v[190:191], v[158:159], v[188:189], v[148:149] op_sel_hi:[0,1,1]
	v_pk_fma_f32 v[148:149], v[58:59], v[174:175], v[154:155] op_sel_hi:[0,1,1]
	v_mov_b32_e32 v154, v61
	v_pk_fma_f32 v[152:153], v[58:59], v[174:175], v[152:153] op_sel:[1,0,0]
	v_pk_fma_f32 v[146:147], v[60:61], v[174:175], v[146:147] op_sel_hi:[0,1,1]
	v_pk_fma_f32 v[140:141], v[154:155], v[174:175], v[140:141] op_sel_hi:[0,1,1]
	v_mov_b32_e32 v194, v65
	v_pk_fma_f32 v[150:151], v[34:35], v[174:175], v[150:151] op_sel_hi:[0,1,1]
	v_pk_fma_f32 v[144:145], v[34:35], v[174:175], v[144:145] op_sel:[1,0,0]
	v_pk_fma_f32 v[138:139], v[36:37], v[174:175], v[138:139] op_sel_hi:[0,1,1]
	s_waitcnt vmcnt(2)
	v_cvt_f32_f16_sdwa v193, v26 dst_sel:DWORD dst_unused:UNUSED_PAD src0_sel:WORD_1
	v_cvt_f32_f16_e32 v192, v26
	v_pk_fma_f32 v[148:149], v[62:63], v[176:177], v[148:149] op_sel_hi:[0,1,1]
	v_pk_fma_f32 v[152:153], v[62:63], v[176:177], v[152:153] op_sel:[1,0,0]
	v_pk_fma_f32 v[146:147], v[64:65], v[176:177], v[146:147] op_sel_hi:[0,1,1]
	v_pk_fma_f32 v[140:141], v[194:195], v[176:177], v[140:141] op_sel_hi:[0,1,1]
	v_mov_b32_e32 v196, v69
	v_pk_fma_f32 v[150:151], v[38:39], v[176:177], v[150:151] op_sel_hi:[0,1,1]
	v_pk_fma_f32 v[144:145], v[38:39], v[176:177], v[144:145] op_sel:[1,0,0]
	v_pk_fma_f32 v[138:139], v[40:41], v[176:177], v[138:139] op_sel_hi:[0,1,1]
	v_cvt_f32_f16_sdwa v175, v3 dst_sel:DWORD dst_unused:UNUSED_PAD src0_sel:WORD_1
	v_cvt_f32_f16_e32 v174, v3
	v_pk_fma_f32 v[148:149], v[66:67], v[178:179], v[148:149] op_sel_hi:[0,1,1]
	v_pk_fma_f32 v[152:153], v[66:67], v[178:179], v[152:153] op_sel:[1,0,0]
	v_pk_fma_f32 v[146:147], v[68:69], v[178:179], v[146:147] op_sel_hi:[0,1,1]
	v_pk_fma_f32 v[140:141], v[196:197], v[178:179], v[140:141] op_sel_hi:[0,1,1]
	v_mov_b32_e32 v198, v73
	v_pk_fma_f32 v[150:151], v[42:43], v[178:179], v[150:151] op_sel_hi:[0,1,1]
	v_pk_fma_f32 v[144:145], v[42:43], v[178:179], v[144:145] op_sel:[1,0,0]
	v_pk_fma_f32 v[138:139], v[44:45], v[178:179], v[138:139] op_sel_hi:[0,1,1]
	v_cvt_f32_f16_sdwa v179, v7 dst_sel:DWORD dst_unused:UNUSED_PAD src0_sel:WORD_1
	v_cvt_f32_f16_e32 v178, v7
	v_pk_fma_f32 v[148:149], v[70:71], v[180:181], v[148:149] op_sel_hi:[0,1,1]
	v_pk_fma_f32 v[152:153], v[70:71], v[180:181], v[152:153] op_sel:[1,0,0]
	v_pk_fma_f32 v[146:147], v[72:73], v[180:181], v[146:147] op_sel_hi:[0,1,1]
	v_pk_fma_f32 v[140:141], v[198:199], v[180:181], v[140:141] op_sel_hi:[0,1,1]
	v_mov_b32_e32 v200, v77
	v_pk_fma_f32 v[150:151], v[46:47], v[180:181], v[150:151] op_sel_hi:[0,1,1]
	v_pk_fma_f32 v[144:145], v[46:47], v[180:181], v[144:145] op_sel:[1,0,0]
	v_pk_fma_f32 v[138:139], v[48:49], v[180:181], v[138:139] op_sel_hi:[0,1,1]
	v_cvt_f32_f16_sdwa v181, v11 dst_sel:DWORD dst_unused:UNUSED_PAD src0_sel:WORD_1
	v_cvt_f32_f16_e32 v180, v11
	v_pk_fma_f32 v[148:149], v[74:75], v[188:189], v[148:149] op_sel_hi:[0,1,1]
	v_pk_fma_f32 v[152:153], v[74:75], v[188:189], v[152:153] op_sel:[1,0,0]
	v_pk_fma_f32 v[146:147], v[76:77], v[188:189], v[146:147] op_sel_hi:[0,1,1]
	v_pk_fma_f32 v[140:141], v[200:201], v[188:189], v[140:141] op_sel_hi:[0,1,1]
	v_pk_fma_f32 v[150:151], v[50:51], v[188:189], v[150:151] op_sel_hi:[0,1,1]
	v_pk_fma_f32 v[144:145], v[50:51], v[188:189], v[144:145] op_sel:[1,0,0]
	v_pk_fma_f32 v[138:139], v[52:53], v[188:189], v[138:139] op_sel_hi:[0,1,1]
	s_waitcnt lgkmcnt(0)
; __device__ __forceinline__ void dsa_item(const KP& p, int b, int tile, char* smem) {
;     ...
; #pragma unroll
;         for (int i = 0; i < 8; ++i) {
;           const int pos = (g8 * 8 + i) * 8 + rs;
;           const f32x4 pa = *(const f32x4*)&pbuf[pos * 8];
;           const f32x4 pb = *(const f32x4*)&pbuf[pos * 8 + 4];
;           float vf[8];
; #pragma unroll
;           for (int e = 0; e < 8; ++e) vf[e] = (float)vv[i][e];
; #pragma unroll
;           for (int e = 0; e < 8; ++e) {
;             acc[0][e] += pa[0] * vf[e]; acc[1][e] += pa[1] * vf[e]; acc[2][e] += pa[2] * vf[e]; acc[3][e] += pa[3] * vf[e];
;             acc[4][e] += pb[0] * vf[e]; acc[5][e] += pb[1] * vf[e]; acc[6][e] += pb[2] * vf[e]; acc[7][e] += pb[3] * vf[e];
;           }
;         }
	v_mov_b32_e32 v176, v57
	v_cvt_f32_f16_sdwa v189, v15 dst_sel:DWORD dst_unused:UNUSED_PAD src0_sel:WORD_1
	v_cvt_f32_f16_e32 v188, v15
	v_pk_fma_f32 v[2:3], v[56:57], v[192:193], v[138:139] op_sel_hi:[0,1,1]
	v_pk_fma_f32 v[138:139], v[176:177], v[192:193], v[190:191] op_sel_hi:[0,1,1]
	v_pk_fma_f32 v[132:133], v[156:157], v[174:175], v[132:133] op_sel_hi:[0,1,1]
	v_cvt_f32_f16_sdwa v191, v23 dst_sel:DWORD dst_unused:UNUSED_PAD src0_sel:WORD_1
	v_cvt_f32_f16_e32 v190, v23
	v_pk_fma_f32 v[14:15], v[6:7], v[178:179], v[132:133] op_sel_hi:[0,1,1]
	v_mov_b32_e32 v202, v81
	v_pk_fma_f32 v[14:15], v[10:11], v[180:181], v[14:15] op_sel_hi:[0,1,1]
	v_pk_fma_f32 v[148:149], v[78:79], v[192:193], v[148:149] op_sel_hi:[0,1,1]
	v_pk_fma_f32 v[152:153], v[78:79], v[192:193], v[152:153] op_sel:[1,0,0]
	v_pk_fma_f32 v[146:147], v[80:81], v[192:193], v[146:147] op_sel_hi:[0,1,1]
	v_pk_fma_f32 v[140:141], v[202:203], v[192:193], v[140:141] op_sel_hi:[0,1,1]
	v_pk_fma_f32 v[150:151], v[54:55], v[192:193], v[150:151] op_sel_hi:[0,1,1]
	v_pk_fma_f32 v[144:145], v[54:55], v[192:193], v[144:145] op_sel:[1,0,0]
	v_pk_fma_f32 v[14:15], v[22:23], v[188:189], v[14:15] op_sel_hi:[0,1,1]
	v_cvt_f32_f16_sdwa v193, v27 dst_sel:DWORD dst_unused:UNUSED_PAD src0_sel:WORD_1
	v_cvt_f32_f16_e32 v192, v27
	v_pk_fma_f32 v[26:27], v[58:59], v[174:175], v[134:135] op_sel:[1,0,0]
	v_pk_fma_f32 v[134:135], v[34:35], v[174:175], v[136:137] op_sel_hi:[0,1,1]
	v_cvt_f32_f16_sdwa v137, v4 dst_sel:DWORD dst_unused:UNUSED_PAD src0_sel:WORD_1
	v_cvt_f32_f16_e32 v136, v4
	v_pk_fma_f32 v[132:133], v[158:159], v[190:191], v[14:15] op_sel_hi:[0,1,1]
	v_pk_fma_f32 v[14:15], v[58:59], v[174:175], v[142:143] op_sel_hi:[0,1,1]
	v_cvt_f32_f16_sdwa v143, v8 dst_sel:DWORD dst_unused:UNUSED_PAD src0_sel:WORD_1
	v_cvt_f32_f16_e32 v142, v8
	v_pk_fma_f32 v[128:129], v[60:61], v[174:175], v[128:129] op_sel_hi:[0,1,1]
	v_pk_fma_f32 v[120:121], v[154:155], v[174:175], v[120:121] op_sel_hi:[0,1,1]
	v_pk_fma_f32 v[130:131], v[34:35], v[174:175], v[130:131] op_sel:[1,0,0]
	v_pk_fma_f32 v[122:123], v[36:37], v[174:175], v[122:123] op_sel_hi:[0,1,1]
	v_cvt_f32_f16_sdwa v175, v12 dst_sel:DWORD dst_unused:UNUSED_PAD src0_sel:WORD_1
	v_cvt_f32_f16_e32 v174, v12
	v_pk_fma_f32 v[14:15], v[62:63], v[178:179], v[14:15] op_sel_hi:[0,1,1]
	v_pk_fma_f32 v[26:27], v[62:63], v[178:179], v[26:27] op_sel:[1,0,0]
	v_pk_fma_f32 v[128:129], v[64:65], v[178:179], v[128:129] op_sel_hi:[0,1,1]
	v_pk_fma_f32 v[120:121], v[194:195], v[178:179], v[120:121] op_sel_hi:[0,1,1]
	v_pk_fma_f32 v[134:135], v[38:39], v[178:179], v[134:135] op_sel_hi:[0,1,1]
	v_pk_fma_f32 v[130:131], v[38:39], v[178:179], v[130:131] op_sel:[1,0,0]
	v_pk_fma_f32 v[122:123], v[40:41], v[178:179], v[122:123] op_sel_hi:[0,1,1]
	v_cvt_f32_f16_sdwa v179, v16 dst_sel:DWORD dst_unused:UNUSED_PAD src0_sel:WORD_1
	v_cvt_f32_f16_e32 v178, v16
	v_pk_fma_f32 v[14:15], v[66:67], v[180:181], v[14:15] op_sel_hi:[0,1,1]
	v_pk_fma_f32 v[26:27], v[66:67], v[180:181], v[26:27] op_sel:[1,0,0]
	v_pk_fma_f32 v[128:129], v[68:69], v[180:181], v[128:129] op_sel_hi:[0,1,1]
	v_pk_fma_f32 v[120:121], v[196:197], v[180:181], v[120:121] op_sel_hi:[0,1,1]
	v_pk_fma_f32 v[134:135], v[42:43], v[180:181], v[134:135] op_sel_hi:[0,1,1]
	v_pk_fma_f32 v[130:131], v[42:43], v[180:181], v[130:131] op_sel:[1,0,0]
	v_pk_fma_f32 v[122:123], v[44:45], v[180:181], v[122:123] op_sel_hi:[0,1,1]
	v_cvt_f32_f16_sdwa v181, v24 dst_sel:DWORD dst_unused:UNUSED_PAD src0_sel:WORD_1
	v_cvt_f32_f16_e32 v180, v24
	v_pk_fma_f32 v[106:107], v[36:37], v[136:137], v[106:107] op_sel_hi:[0,1,1]
	v_pk_fma_f32 v[14:15], v[70:71], v[188:189], v[14:15] op_sel_hi:[0,1,1]
	v_pk_fma_f32 v[26:27], v[70:71], v[188:189], v[26:27] op_sel:[1,0,0]
	v_pk_fma_f32 v[128:129], v[72:73], v[188:189], v[128:129] op_sel_hi:[0,1,1]
	v_pk_fma_f32 v[120:121], v[198:199], v[188:189], v[120:121] op_sel_hi:[0,1,1]
	v_pk_fma_f32 v[134:135], v[46:47], v[188:189], v[134:135] op_sel_hi:[0,1,1]
	v_pk_fma_f32 v[130:131], v[46:47], v[188:189], v[130:131] op_sel:[1,0,0]
	v_pk_fma_f32 v[122:123], v[48:49], v[188:189], v[122:123] op_sel_hi:[0,1,1]
	v_pk_fma_f32 v[114:115], v[156:157], v[136:137], v[114:115] op_sel_hi:[0,1,1]
	v_cvt_f32_f16_sdwa v189, v28 dst_sel:DWORD dst_unused:UNUSED_PAD src0_sel:WORD_1
	v_cvt_f32_f16_e32 v188, v28
	v_pk_fma_f32 v[124:125], v[58:59], v[136:137], v[124:125] op_sel_hi:[0,1,1]
	v_pk_fma_f32 v[116:117], v[58:59], v[136:137], v[116:117] op_sel:[1,0,0]
	v_pk_fma_f32 v[110:111], v[60:61], v[136:137], v[110:111] op_sel_hi:[0,1,1]
	v_pk_fma_f32 v[104:105], v[154:155], v[136:137], v[104:105] op_sel_hi:[0,1,1]
	v_pk_fma_f32 v[118:119], v[34:35], v[136:137], v[118:119] op_sel_hi:[0,1,1]
	v_pk_fma_f32 v[112:113], v[34:35], v[136:137], v[112:113] op_sel:[1,0,0]
	v_pk_fma_f32 v[106:107], v[40:41], v[142:143], v[106:107] op_sel_hi:[0,1,1]
	v_cvt_f32_f16_sdwa v137, v5 dst_sel:DWORD dst_unused:UNUSED_PAD src0_sel:WORD_1
	v_cvt_f32_f16_e32 v136, v5
	v_pk_fma_f32 v[106:107], v[44:45], v[174:175], v[106:107] op_sel_hi:[0,1,1]
	v_pk_fma_f32 v[106:107], v[48:49], v[178:179], v[106:107] op_sel_hi:[0,1,1]
	v_pk_fma_f32 v[4:5], v[52:53], v[180:181], v[106:107] op_sel_hi:[0,1,1]
	v_pk_fma_f32 v[106:107], v[56:57], v[188:189], v[4:5] op_sel_hi:[0,1,1]
	v_pk_fma_f32 v[4:5], v[156:157], v[136:137], v[98:99] op_sel_hi:[0,1,1]
	v_cvt_f32_f16_sdwa v99, v9 dst_sel:DWORD dst_unused:UNUSED_PAD src0_sel:WORD_1
	v_cvt_f32_f16_e32 v98, v9
	v_cvt_f32_f16_sdwa v9, v13 dst_sel:DWORD dst_unused:UNUSED_PAD src0_sel:WORD_1
	v_cvt_f32_f16_e32 v8, v13
	v_cvt_f32_f16_sdwa v13, v17 dst_sel:DWORD dst_unused:UNUSED_PAD src0_sel:WORD_1
	v_cvt_f32_f16_e32 v12, v17
; __device__ __forceinline__ void dsa_item(const KP& p, int b, int tile, char* smem) {
;     ...
; #pragma unroll
;         for (int i = 0; i < 8; ++i) {
;           const int pos = (g8 * 8 + i) * 8 + rs;
;           const f32x4 pa = *(const f32x4*)&pbuf[pos * 8];
;           const f32x4 pb = *(const f32x4*)&pbuf[pos * 8 + 4];
;           float vf[8];
; #pragma unroll
;           for (int e = 0; e < 8; ++e) vf[e] = (float)vv[i][e];
; #pragma unroll
;           for (int e = 0; e < 8; ++e) {
;             acc[0][e] += pa[0] * vf[e]; acc[1][e] += pa[1] * vf[e]; acc[2][e] += pa[2] * vf[e]; acc[3][e] += pa[3] * vf[e];
;             acc[4][e] += pb[0] * vf[e]; acc[5][e] += pb[1] * vf[e]; acc[6][e] += pb[2] * vf[e]; acc[7][e] += pb[3] * vf[e];
;           }
;         }
	v_cvt_f32_f16_sdwa v17, v25 dst_sel:DWORD dst_unused:UNUSED_PAD src0_sel:WORD_1
	v_cvt_f32_f16_e32 v16, v25
	v_pk_fma_f32 v[4:5], v[6:7], v[98:99], v[4:5] op_sel_hi:[0,1,1]
	v_pk_fma_f32 v[114:115], v[6:7], v[142:143], v[114:115] op_sel_hi:[0,1,1]
	v_pk_fma_f32 v[4:5], v[10:11], v[8:9], v[4:5] op_sel_hi:[0,1,1]
	v_pk_fma_f32 v[114:115], v[10:11], v[174:175], v[114:115] op_sel_hi:[0,1,1]
	v_pk_fma_f32 v[4:5], v[22:23], v[12:13], v[4:5] op_sel_hi:[0,1,1]
	v_pk_fma_f32 v[114:115], v[22:23], v[178:179], v[114:115] op_sel_hi:[0,1,1]
	v_pk_fma_f32 v[22:23], v[158:159], v[16:17], v[4:5] op_sel_hi:[0,1,1]
	v_pk_fma_f32 v[4:5], v[58:59], v[136:137], v[108:109] op_sel_hi:[0,1,1]
	v_cvt_f32_f16_sdwa v25, v29 dst_sel:DWORD dst_unused:UNUSED_PAD src0_sel:WORD_1
	v_cvt_f32_f16_e32 v24, v29
	v_pk_fma_f32 v[4:5], v[62:63], v[98:99], v[4:5] op_sel_hi:[0,1,1]
	v_pk_fma_f32 v[4:5], v[66:67], v[8:9], v[4:5] op_sel_hi:[0,1,1]
	v_pk_fma_f32 v[4:5], v[70:71], v[12:13], v[4:5] op_sel_hi:[0,1,1]
	v_pk_fma_f32 v[4:5], v[74:75], v[16:17], v[4:5] op_sel_hi:[0,1,1]
	v_pk_fma_f32 v[28:29], v[78:79], v[24:25], v[4:5] op_sel_hi:[0,1,1]
	v_pk_fma_f32 v[4:5], v[58:59], v[136:137], v[100:101] op_sel:[1,0,0]
	v_pk_fma_f32 v[124:125], v[62:63], v[142:143], v[124:125] op_sel_hi:[0,1,1]
	v_pk_fma_f32 v[4:5], v[62:63], v[98:99], v[4:5] op_sel:[1,0,0]
	v_pk_fma_f32 v[116:117], v[62:63], v[142:143], v[116:117] op_sel:[1,0,0]
	v_pk_fma_f32 v[4:5], v[66:67], v[8:9], v[4:5] op_sel:[1,0,0]
	v_pk_fma_f32 v[110:111], v[64:65], v[142:143], v[110:111] op_sel_hi:[0,1,1]
	v_pk_fma_f32 v[4:5], v[70:71], v[12:13], v[4:5] op_sel:[1,0,0]
	v_pk_fma_f32 v[118:119], v[38:39], v[142:143], v[118:119] op_sel_hi:[0,1,1]
	v_pk_fma_f32 v[4:5], v[74:75], v[16:17], v[4:5] op_sel:[1,0,0]
	v_pk_fma_f32 v[112:113], v[38:39], v[142:143], v[112:113] op_sel:[1,0,0]
	v_pk_fma_f32 v[58:59], v[78:79], v[24:25], v[4:5] op_sel:[1,0,0]
	v_pk_fma_f32 v[4:5], v[60:61], v[136:137], v[94:95] op_sel_hi:[0,1,1]
	v_pk_fma_f32 v[4:5], v[64:65], v[98:99], v[4:5] op_sel_hi:[0,1,1]
	v_pk_fma_f32 v[4:5], v[68:69], v[8:9], v[4:5] op_sel_hi:[0,1,1]
	v_pk_fma_f32 v[4:5], v[72:73], v[12:13], v[4:5] op_sel_hi:[0,1,1]
	v_pk_fma_f32 v[4:5], v[76:77], v[16:17], v[4:5] op_sel_hi:[0,1,1]
	v_pk_fma_f32 v[60:61], v[80:81], v[24:25], v[4:5] op_sel_hi:[0,1,1]
	v_pk_fma_f32 v[4:5], v[154:155], v[136:137], v[90:91] op_sel_hi:[0,1,1]
	v_pk_fma_f32 v[4:5], v[194:195], v[98:99], v[4:5] op_sel_hi:[0,1,1]
	v_pk_fma_f32 v[4:5], v[196:197], v[8:9], v[4:5] op_sel_hi:[0,1,1]
	v_pk_fma_f32 v[4:5], v[198:199], v[12:13], v[4:5] op_sel_hi:[0,1,1]
	v_pk_fma_f32 v[4:5], v[200:201], v[16:17], v[4:5] op_sel_hi:[0,1,1]
	v_pk_fma_f32 v[62:63], v[202:203], v[24:25], v[4:5] op_sel_hi:[0,1,1]
	v_pk_fma_f32 v[4:5], v[34:35], v[136:137], v[102:103] op_sel_hi:[0,1,1]
	v_pk_fma_f32 v[4:5], v[38:39], v[98:99], v[4:5] op_sel_hi:[0,1,1]
	v_pk_fma_f32 v[4:5], v[42:43], v[8:9], v[4:5] op_sel_hi:[0,1,1]
	v_pk_fma_f32 v[4:5], v[46:47], v[12:13], v[4:5] op_sel_hi:[0,1,1]
	v_pk_fma_f32 v[4:5], v[50:51], v[16:17], v[4:5] op_sel_hi:[0,1,1]
	v_pk_fma_f32 v[64:65], v[54:55], v[24:25], v[4:5] op_sel_hi:[0,1,1]
	v_pk_fma_f32 v[4:5], v[34:35], v[136:137], v[96:97] op_sel:[1,0,0]
	v_pk_fma_f32 v[118:119], v[42:43], v[174:175], v[118:119] op_sel_hi:[0,1,1]
	v_pk_fma_f32 v[4:5], v[38:39], v[98:99], v[4:5] op_sel:[1,0,0]
	v_pk_fma_f32 v[112:113], v[42:43], v[174:175], v[112:113] op_sel:[1,0,0]
	v_pk_fma_f32 v[4:5], v[42:43], v[8:9], v[4:5] op_sel:[1,0,0]
	v_pk_fma_f32 v[118:119], v[46:47], v[178:179], v[118:119] op_sel_hi:[0,1,1]
	v_pk_fma_f32 v[4:5], v[46:47], v[12:13], v[4:5] op_sel:[1,0,0]
	v_pk_fma_f32 v[112:113], v[46:47], v[178:179], v[112:113] op_sel:[1,0,0]
	v_pk_fma_f32 v[4:5], v[50:51], v[16:17], v[4:5] op_sel:[1,0,0]
	s_waitcnt vmcnt(1)
	v_cvt_f32_f16_sdwa v43, v19 dst_sel:DWORD dst_unused:UNUSED_PAD src0_sel:WORD_1
	v_pk_fma_f32 v[34:35], v[54:55], v[24:25], v[4:5] op_sel:[1,0,0]
	v_pk_fma_f32 v[4:5], v[36:37], v[136:137], v[92:93] op_sel_hi:[0,1,1]
	v_pk_fma_f32 v[4:5], v[40:41], v[98:99], v[4:5] op_sel_hi:[0,1,1]
	v_pk_fma_f32 v[4:5], v[44:45], v[8:9], v[4:5] op_sel_hi:[0,1,1]
	v_pk_fma_f32 v[4:5], v[48:49], v[12:13], v[4:5] op_sel_hi:[0,1,1]
	v_pk_fma_f32 v[4:5], v[52:53], v[16:17], v[4:5] op_sel_hi:[0,1,1]
	v_pk_fma_f32 v[12:13], v[56:57], v[24:25], v[4:5] op_sel_hi:[0,1,1]
	ds_read_b128 v[4:7], v172 offset:1536
	ds_read_b128 v[8:11], v172 offset:1552
	v_pk_fma_f32 v[24:25], v[176:177], v[24:25], v[22:23] op_sel_hi:[0,1,1]
	v_cvt_f32_f16_sdwa v37, v18 dst_sel:DWORD dst_unused:UNUSED_PAD src0_sel:WORD_1
	v_cvt_f32_f16_e32 v36, v18
	v_cvt_f32_f16_e32 v42, v19
	v_cvt_f32_f16_sdwa v45, v20 dst_sel:DWORD dst_unused:UNUSED_PAD src0_sel:WORD_1
	v_cvt_f32_f16_e32 v44, v20
	v_cvt_f32_f16_sdwa v47, v21 dst_sel:DWORD dst_unused:UNUSED_PAD src0_sel:WORD_1
	v_cvt_f32_f16_e32 v46, v21
	ds_read_b128 v[16:19], v172 offset:1792
	ds_read_b128 v[20:23], v172 offset:1808
	s_waitcnt vmcnt(0)
; __device__ __forceinline__ void dsa_item(const KP& p, int b, int tile, char* smem) {
;     ...
; #pragma unroll
;         for (int i = 0; i < 8; ++i) {
;           const int pos = (g8 * 8 + i) * 8 + rs;
;           const f32x4 pa = *(const f32x4*)&pbuf[pos * 8];
;           const f32x4 pb = *(const f32x4*)&pbuf[pos * 8 + 4];
;           float vf[8];
; #pragma unroll
;           for (int e = 0; e < 8; ++e) vf[e] = (float)vv[i][e];
; #pragma unroll
;           for (int e = 0; e < 8; ++e) {
;             acc[0][e] += pa[0] * vf[e]; acc[1][e] += pa[1] * vf[e]; acc[2][e] += pa[2] * vf[e]; acc[3][e] += pa[3] * vf[e];
;             acc[4][e] += pb[0] * vf[e]; acc[5][e] += pb[1] * vf[e]; acc[6][e] += pb[2] * vf[e]; acc[7][e] += pb[3] * vf[e];
;           }
;         }
	v_cvt_f32_f16_e32 v48, v30
	v_cvt_f32_f16_sdwa v49, v30 dst_sel:DWORD dst_unused:UNUSED_PAD src0_sel:WORD_1
	v_pk_fma_f32 v[124:125], v[66:67], v[174:175], v[124:125] op_sel_hi:[0,1,1]
	v_pk_fma_f32 v[116:117], v[66:67], v[174:175], v[116:117] op_sel:[1,0,0]
	v_pk_fma_f32 v[110:111], v[68:69], v[174:175], v[110:111] op_sel_hi:[0,1,1]
	v_pk_fma_f32 v[104:105], v[194:195], v[142:143], v[104:105] op_sel_hi:[0,1,1]
	v_cvt_f32_f16_e32 v30, v31
	v_cvt_f32_f16_sdwa v31, v31 dst_sel:DWORD dst_unused:UNUSED_PAD src0_sel:WORD_1
	v_pk_fma_f32 v[14:15], v[74:75], v[190:191], v[14:15] op_sel_hi:[0,1,1]
	v_pk_fma_f32 v[26:27], v[74:75], v[190:191], v[26:27] op_sel:[1,0,0]
	v_pk_fma_f32 v[128:129], v[76:77], v[190:191], v[128:129] op_sel_hi:[0,1,1]
	v_pk_fma_f32 v[134:135], v[50:51], v[190:191], v[134:135] op_sel_hi:[0,1,1]
	v_pk_fma_f32 v[130:131], v[50:51], v[190:191], v[130:131] op_sel:[1,0,0]
	v_pk_fma_f32 v[124:125], v[70:71], v[178:179], v[124:125] op_sel_hi:[0,1,1]
	v_pk_fma_f32 v[116:117], v[70:71], v[178:179], v[116:117] op_sel:[1,0,0]
	v_pk_fma_f32 v[110:111], v[72:73], v[178:179], v[110:111] op_sel_hi:[0,1,1]
	v_pk_fma_f32 v[104:105], v[196:197], v[174:175], v[104:105] op_sel_hi:[0,1,1]
	v_pk_fma_f32 v[118:119], v[50:51], v[180:181], v[118:119] op_sel_hi:[0,1,1]
	v_pk_fma_f32 v[112:113], v[50:51], v[180:181], v[112:113] op_sel:[1,0,0]
	v_cvt_f32_f16_e32 v50, v32
	v_cvt_f32_f16_sdwa v51, v32 dst_sel:DWORD dst_unused:UNUSED_PAD src0_sel:WORD_1
	v_pk_fma_f32 v[14:15], v[78:79], v[192:193], v[14:15] op_sel_hi:[0,1,1]
	v_pk_fma_f32 v[26:27], v[78:79], v[192:193], v[26:27] op_sel:[1,0,0]
	v_pk_fma_f32 v[128:129], v[80:81], v[192:193], v[128:129] op_sel_hi:[0,1,1]
	v_pk_fma_f32 v[120:121], v[200:201], v[190:191], v[120:121] op_sel_hi:[0,1,1]
	v_pk_fma_f32 v[122:123], v[52:53], v[190:191], v[122:123] op_sel_hi:[0,1,1]
	v_pk_fma_f32 v[124:125], v[74:75], v[180:181], v[124:125] op_sel_hi:[0,1,1]
	v_pk_fma_f32 v[116:117], v[74:75], v[180:181], v[116:117] op_sel:[1,0,0]
	v_pk_fma_f32 v[110:111], v[76:77], v[180:181], v[110:111] op_sel_hi:[0,1,1]
	v_pk_fma_f32 v[104:105], v[198:199], v[178:179], v[104:105] op_sel_hi:[0,1,1]
	s_waitcnt lgkmcnt(3)
	v_mov_b32_e32 v38, v7
	s_waitcnt lgkmcnt(2)
	v_mov_b32_e32 v40, v11
	v_cvt_f32_f16_e32 v32, v33
	v_cvt_f32_f16_sdwa v33, v33 dst_sel:DWORD dst_unused:UNUSED_PAD src0_sel:WORD_1
	v_pk_fma_f32 v[2:3], v[10:11], v[36:37], v[2:3] op_sel_hi:[0,1,1]
	v_pk_fma_f32 v[120:121], v[202:203], v[192:193], v[120:121] op_sel_hi:[0,1,1]
	v_pk_fma_f32 v[134:135], v[54:55], v[192:193], v[134:135] op_sel_hi:[0,1,1]
	v_pk_fma_f32 v[130:131], v[54:55], v[192:193], v[130:131] op_sel:[1,0,0]
	v_pk_fma_f32 v[122:123], v[56:57], v[192:193], v[122:123] op_sel_hi:[0,1,1]
	v_pk_fma_f32 v[132:133], v[176:177], v[192:193], v[132:133] op_sel_hi:[0,1,1]
	v_pk_fma_f32 v[114:115], v[158:159], v[180:181], v[114:115] op_sel_hi:[0,1,1]
	v_pk_fma_f32 v[124:125], v[78:79], v[188:189], v[124:125] op_sel_hi:[0,1,1]
	v_pk_fma_f32 v[116:117], v[78:79], v[188:189], v[116:117] op_sel:[1,0,0]
	v_pk_fma_f32 v[110:111], v[80:81], v[188:189], v[110:111] op_sel_hi:[0,1,1]
	v_pk_fma_f32 v[104:105], v[200:201], v[180:181], v[104:105] op_sel_hi:[0,1,1]
	v_pk_fma_f32 v[118:119], v[54:55], v[188:189], v[118:119] op_sel_hi:[0,1,1]
	v_pk_fma_f32 v[112:113], v[54:55], v[188:189], v[112:113] op_sel:[1,0,0]
	v_pk_fma_f32 v[52:53], v[4:5], v[36:37], v[148:149] op_sel_hi:[0,1,1]
	v_pk_fma_f32 v[54:55], v[4:5], v[36:37], v[152:153] op_sel:[1,0,0]
	v_pk_fma_f32 v[56:57], v[6:7], v[36:37], v[146:147] op_sel_hi:[0,1,1]
	v_pk_fma_f32 v[66:67], v[38:39], v[36:37], v[140:141] op_sel_hi:[0,1,1]
	v_pk_fma_f32 v[68:69], v[8:9], v[36:37], v[150:151] op_sel_hi:[0,1,1]
	v_pk_fma_f32 v[70:71], v[8:9], v[36:37], v[144:145] op_sel:[1,0,0]
	v_pk_fma_f32 v[36:37], v[40:41], v[36:37], v[138:139] op_sel_hi:[0,1,1]
	s_waitcnt lgkmcnt(1)
	v_mov_b32_e32 v72, v19
	s_waitcnt lgkmcnt(0)
; __device__ __forceinline__ void dsa_item(const KP& p, int b, int tile, char* smem) {
;     ...
;       for (int g8 = 0; g8 < 4; ++g8) {
;         h8 vv[8];
; #pragma unroll
;         for (int i = 0; i < 8; ++i) {
;           const int pos = (g8 * 8 + i) * 8 + rs;
;           const int s = (pos < nsel) ? (int)sel[tk * 256 + pos] : 0;
;           vv[i] = *(const h8*)(ub + (size_t)s * NU + C_BV + dc * 8);
;         }
; #pragma unroll
;         for (int i = 0; i < 8; ++i) {
;           const int pos = (g8 * 8 + i) * 8 + rs;
;           const f32x4 pa = *(const f32x4*)&pbuf[pos * 8];
;           const f32x4 pb = *(const f32x4*)&pbuf[pos * 8 + 4];
;           float vf[8];
; #pragma unroll
;           for (int e = 0; e < 8; ++e) vf[e] = (float)vv[i][e];
; #pragma unroll
;           for (int e = 0; e < 8; ++e) {
;             acc[0][e] += pa[0] * vf[e]; acc[1][e] += pa[1] * vf[e]; acc[2][e] += pa[2] * vf[e]; acc[3][e] += pa[3] * vf[e];
;             acc[4][e] += pb[0] * vf[e]; acc[5][e] += pb[1] * vf[e]; acc[6][e] += pb[2] * vf[e]; acc[7][e] += pb[3] * vf[e];
;           }
;         }
	v_mov_b32_e32 v74, v23
	v_pk_fma_f32 v[138:139], v[22:23], v[48:49], v[2:3] op_sel_hi:[0,1,1]
	v_pk_fma_f32 v[2:3], v[4:5], v[42:43], v[14:15] op_sel_hi:[0,1,1]
	v_pk_fma_f32 v[14:15], v[4:5], v[42:43], v[26:27] op_sel:[1,0,0]
	v_pk_fma_f32 v[26:27], v[6:7], v[42:43], v[128:129] op_sel_hi:[0,1,1]
	v_pk_fma_f32 v[104:105], v[202:203], v[188:189], v[104:105] op_sel_hi:[0,1,1]
	v_pk_fma_f32 v[114:115], v[176:177], v[188:189], v[114:115] op_sel_hi:[0,1,1]
	v_pk_fma_f32 v[154:155], v[16:17], v[48:49], v[52:53] op_sel_hi:[0,1,1]
	v_pk_fma_f32 v[152:153], v[16:17], v[48:49], v[54:55] op_sel:[1,0,0]
	v_pk_fma_f32 v[146:147], v[18:19], v[48:49], v[56:57] op_sel_hi:[0,1,1]
	v_pk_fma_f32 v[140:141], v[72:73], v[48:49], v[66:67] op_sel_hi:[0,1,1]
	v_pk_fma_f32 v[150:151], v[20:21], v[48:49], v[68:69] op_sel_hi:[0,1,1]
	v_pk_fma_f32 v[144:145], v[20:21], v[48:49], v[70:71] op_sel:[1,0,0]
	v_pk_fma_f32 v[148:149], v[74:75], v[48:49], v[36:37] op_sel_hi:[0,1,1]
	v_pk_fma_f32 v[36:37], v[38:39], v[42:43], v[120:121] op_sel_hi:[0,1,1]
	v_pk_fma_f32 v[48:49], v[8:9], v[42:43], v[134:135] op_sel_hi:[0,1,1]
	v_pk_fma_f32 v[52:53], v[8:9], v[42:43], v[130:131] op_sel:[1,0,0]
	v_pk_fma_f32 v[54:55], v[10:11], v[42:43], v[122:123] op_sel_hi:[0,1,1]
	v_pk_fma_f32 v[42:43], v[40:41], v[42:43], v[132:133] op_sel_hi:[0,1,1]
	v_pk_fma_f32 v[142:143], v[16:17], v[30:31], v[2:3] op_sel_hi:[0,1,1]
	v_pk_fma_f32 v[134:135], v[16:17], v[30:31], v[14:15] op_sel:[1,0,0]
	v_pk_fma_f32 v[128:129], v[18:19], v[30:31], v[26:27] op_sel_hi:[0,1,1]
	v_pk_fma_f32 v[2:3], v[4:5], v[44:45], v[124:125] op_sel_hi:[0,1,1]
	v_pk_fma_f32 v[14:15], v[4:5], v[44:45], v[116:117] op_sel:[1,0,0]
	v_pk_fma_f32 v[26:27], v[6:7], v[44:45], v[110:111] op_sel_hi:[0,1,1]
	v_pk_fma_f32 v[120:121], v[72:73], v[30:31], v[36:37] op_sel_hi:[0,1,1]
	v_pk_fma_f32 v[136:137], v[20:21], v[30:31], v[48:49] op_sel_hi:[0,1,1]
	v_pk_fma_f32 v[130:131], v[20:21], v[30:31], v[52:53] op_sel:[1,0,0]
	v_pk_fma_f32 v[122:123], v[22:23], v[30:31], v[54:55] op_sel_hi:[0,1,1]
	v_pk_fma_f32 v[132:133], v[74:75], v[30:31], v[42:43] op_sel_hi:[0,1,1]
	v_pk_fma_f32 v[30:31], v[38:39], v[44:45], v[104:105] op_sel_hi:[0,1,1]
	v_pk_fma_f32 v[36:37], v[8:9], v[44:45], v[118:119] op_sel_hi:[0,1,1]
	v_pk_fma_f32 v[42:43], v[8:9], v[44:45], v[112:113] op_sel:[1,0,0]
	v_pk_fma_f32 v[48:49], v[10:11], v[44:45], v[106:107] op_sel_hi:[0,1,1]
	v_pk_fma_f32 v[44:45], v[40:41], v[44:45], v[114:115] op_sel_hi:[0,1,1]
	v_pk_fma_f32 v[124:125], v[16:17], v[50:51], v[2:3] op_sel_hi:[0,1,1]
	v_pk_fma_f32 v[116:117], v[16:17], v[50:51], v[14:15] op_sel:[1,0,0]
	v_pk_fma_f32 v[110:111], v[18:19], v[50:51], v[26:27] op_sel_hi:[0,1,1]
	v_pk_fma_f32 v[2:3], v[4:5], v[46:47], v[28:29] op_sel_hi:[0,1,1]
	v_pk_fma_f32 v[4:5], v[4:5], v[46:47], v[58:59] op_sel:[1,0,0]
	v_pk_fma_f32 v[6:7], v[6:7], v[46:47], v[60:61] op_sel_hi:[0,1,1]
	v_pk_fma_f32 v[14:15], v[38:39], v[46:47], v[62:63] op_sel_hi:[0,1,1]
	v_pk_fma_f32 v[26:27], v[8:9], v[46:47], v[64:65] op_sel_hi:[0,1,1]
	v_pk_fma_f32 v[8:9], v[8:9], v[46:47], v[34:35] op_sel:[1,0,0]
	v_pk_fma_f32 v[10:11], v[10:11], v[46:47], v[12:13] op_sel_hi:[0,1,1]
	v_pk_fma_f32 v[12:13], v[40:41], v[46:47], v[24:25] op_sel_hi:[0,1,1]
	s_add_i32 s14, s14, 64
	v_pk_fma_f32 v[104:105], v[72:73], v[50:51], v[30:31] op_sel_hi:[0,1,1]
	v_pk_fma_f32 v[118:119], v[20:21], v[50:51], v[36:37] op_sel_hi:[0,1,1]
	v_pk_fma_f32 v[112:113], v[20:21], v[50:51], v[42:43] op_sel:[1,0,0]
	v_pk_fma_f32 v[106:107], v[22:23], v[50:51], v[48:49] op_sel_hi:[0,1,1]
	v_pk_fma_f32 v[114:115], v[74:75], v[50:51], v[44:45] op_sel_hi:[0,1,1]
	v_pk_fma_f32 v[108:109], v[16:17], v[32:33], v[2:3] op_sel_hi:[0,1,1]
	v_pk_fma_f32 v[100:101], v[16:17], v[32:33], v[4:5] op_sel:[1,0,0]
	v_pk_fma_f32 v[94:95], v[18:19], v[32:33], v[6:7] op_sel_hi:[0,1,1]
	v_pk_fma_f32 v[90:91], v[72:73], v[32:33], v[14:15] op_sel_hi:[0,1,1]
	v_pk_fma_f32 v[102:103], v[20:21], v[32:33], v[26:27] op_sel_hi:[0,1,1]
	v_pk_fma_f32 v[96:97], v[20:21], v[32:33], v[8:9] op_sel:[1,0,0]
	v_pk_fma_f32 v[92:93], v[22:23], v[32:33], v[10:11] op_sel_hi:[0,1,1]
	v_pk_fma_f32 v[98:99], v[74:75], v[32:33], v[12:13] op_sel_hi:[0,1,1]
	v_add_u32_e32 v172, 0x800, v172
	s_cmpk_eq_i32 s14, 0x100
	v_add_u32_e32 v127, 0x80, v127
	s_cbranch_scc1 .LBB0_1424
.LBB0_1513:
	s_add_u32 s2, s78, 0x3880
	s_addc_u32 s3, s79, 0
	ds_read_u16 v2, v127
	ds_read_u16 v6, v127 offset:16
	ds_read_u16 v10, v127 offset:32
	ds_read_u16 v14, v127 offset:48
	ds_read_u16 v22, v127 offset:64
	ds_read_u16 v26, v127 offset:80
	ds_read_u16 v18, v127 offset:96
	ds_read_u16 v30, v127 offset:112
	v_add_u32_e32 v34, s14, v165
	v_cmp_lt_i32_e32 vcc, v34, v85
	s_waitcnt lgkmcnt(7)
	s_nop 0
	v_cndmask_b32_e32 v2, 0, v2, vcc
	v_mul_u32_u24_e32 v2, 0x1d00, v2
	v_lshl_add_u32 v2, v2, 1, v0
	global_load_dwordx4 v[2:5], v2, s[2:3]
	v_add_u32_e32 v35, 8, v34
	v_cmp_lt_i32_e32 vcc, v35, v85
	s_waitcnt lgkmcnt(6)
	s_nop 0
	v_cndmask_b32_e32 v6, 0, v6, vcc
	v_mul_u32_u24_e32 v6, 0x1d00, v6
	v_lshl_add_u32 v6, v6, 1, v0
	global_load_dwordx4 v[6:9], v6, s[2:3]
	v_add_u32_e32 v35, 16, v34
	v_cmp_lt_i32_e32 vcc, v35, v85
	s_waitcnt lgkmcnt(5)
	s_nop 0
	v_cndmask_b32_e32 v10, 0, v10, vcc
	v_mul_u32_u24_e32 v10, 0x1d00, v10
	v_lshl_add_u32 v10, v10, 1, v0
	global_load_dwordx4 v[10:13], v10, s[2:3]
	v_add_u32_e32 v35, 24, v34
	v_cmp_lt_i32_e32 vcc, v35, v85
	s_waitcnt lgkmcnt(4)
	s_nop 0
	v_cndmask_b32_e32 v14, 0, v14, vcc
	v_mul_u32_u24_e32 v14, 0x1d00, v14
	v_lshl_add_u32 v14, v14, 1, v0
	global_load_dwordx4 v[14:17], v14, s[2:3]
	v_add_u32_e32 v35, 32, v34
	v_cmp_lt_i32_e32 vcc, v35, v85
	s_waitcnt lgkmcnt(3)
	s_nop 0
	v_cndmask_b32_e32 v22, 0, v22, vcc
	v_mul_u32_u24_e32 v22, 0x1d00, v22
	v_lshl_add_u32 v22, v22, 1, v0
	global_load_dwordx4 v[22:25], v22, s[2:3]
	v_add_u32_e32 v35, 40, v34
	v_cmp_lt_i32_e32 vcc, v35, v85
	s_waitcnt lgkmcnt(2)
	s_nop 0
	v_cndmask_b32_e32 v26, 0, v26, vcc
	v_mul_u32_u24_e32 v26, 0x1d00, v26
	v_lshl_add_u32 v26, v26, 1, v0
	global_load_dwordx4 v[26:29], v26, s[2:3]
	v_add_u32_e32 v35, 48, v34
	v_cmp_lt_i32_e32 vcc, v35, v85
	s_waitcnt lgkmcnt(1)
	s_nop 0
	v_cndmask_b32_e32 v18, 0, v18, vcc
	v_mul_u32_u24_e32 v18, 0x1d00, v18
	v_lshl_add_u32 v18, v18, 1, v0
	global_load_dwordx4 v[18:21], v18, s[2:3]
	v_add_u32_e32 v35, 56, v34
	v_cmp_lt_i32_e32 vcc, v35, v85
	s_waitcnt lgkmcnt(0)
	s_nop 0
	v_cndmask_b32_e32 v30, 0, v30, vcc
	v_mul_u32_u24_e32 v30, 0x1d00, v30
	v_lshl_add_u32 v30, v30, 1, v0
	global_load_dwordx4 v[30:33], v30, s[2:3]
	s_branch .LBB0_1512
